# leading half runs its epilogue / next-unit setup at s_setprio 2 (set after its align rendezvous, reset by its next MMA segment and at phase end)
# speedup vs baseline: 1.0029x; 1.0002x over previous
.LBB0_246:
	s_add_i32 s76, s88, 2
	s_add_u32 s33, s0, 0xfff80080
	s_addc_u32 s48, s1, -1
	s_add_i32 m0, s35, 0xc000
	s_add_i32 s77, s35, 0xe000
	global_load_lds_dwordx4 v146, s[0:1]
	s_mov_b32 m0, s77
	s_cmp_eq_u32 vcc_hi, s88
	global_load_lds_dwordx4 v148, s[0:1]
	s_cselect_b32 s88, vcc_lo, s56
	s_cselect_b32 s91, s69, s48
	s_cselect_b32 s90, s75, s33
	s_cselect_b32 s89, s73, s57
	s_add_i32 s33, 0, 0x10000
	s_add_i32 s96, 0, 0x14000
	ds_read_b128 v[150:153], v246
	ds_read_b128 v[154:157], v246 offset:1024
	ds_read_b128 v[158:161], v246 offset:2048
	ds_read_b128 v[162:165], v246 offset:3072
	ds_read_b128 v[166:169], v247
	ds_read_b128 v[170:173], v247 offset:1024
	ds_read_b128 v[174:177], v247 offset:2048
	ds_read_b128 v[178:181], v247 offset:3072
	ds_read_b128 v[182:185], v141
	ds_read_b128 v[186:189], v141 offset:1024
	ds_read_b128 v[190:193], v141 offset:2048
	ds_read_b128 v[194:197], v141 offset:3072
	ds_read_b128 v[198:201], v141 offset:4096
	ds_read_b128 v[202:205], v141 offset:5120
	ds_read_b128 v[210:213], v141 offset:6144
	ds_read_b128 v[214:217], v141 offset:7168
	s_waitcnt vmcnt(8)
	s_waitcnt lgkmcnt(0)
	s_setprio 1
	s_barrier
	v_mfma_f32_16x16x32_bf16 v[128:131], v[150:153], v[182:185], v[128:131]
	v_mfma_f32_16x16x32_bf16 v[124:127], v[158:161], v[182:185], v[124:127]
	v_mfma_f32_16x16x32_bf16 v[116:119], v[150:153], v[190:193], v[116:119]
	v_mfma_f32_16x16x32_bf16 v[108:111], v[158:161], v[190:193], v[108:111]
	v_mfma_f32_16x16x32_bf16 v[100:103], v[150:153], v[198:201], v[100:103]
	v_mfma_f32_16x16x32_bf16 v[92:95], v[158:161], v[198:201], v[92:95]
	v_mfma_f32_16x16x32_bf16 v[84:87], v[150:153], v[210:213], v[84:87]
	v_mfma_f32_16x16x32_bf16 v[76:79], v[158:161], v[210:213], v[76:79]
	v_mfma_f32_16x16x32_bf16 v[128:131], v[154:157], v[186:189], v[128:131]
	v_mfma_f32_16x16x32_bf16 v[124:127], v[162:165], v[186:189], v[124:127]
	v_mfma_f32_16x16x32_bf16 v[116:119], v[154:157], v[194:197], v[116:119]
	v_mfma_f32_16x16x32_bf16 v[108:111], v[162:165], v[194:197], v[108:111]
	v_mfma_f32_16x16x32_bf16 v[100:103], v[154:157], v[202:205], v[100:103]
	v_mfma_f32_16x16x32_bf16 v[92:95], v[162:165], v[202:205], v[92:95]
	v_mfma_f32_16x16x32_bf16 v[84:87], v[154:157], v[214:217], v[84:87]
	v_mfma_f32_16x16x32_bf16 v[76:79], v[162:165], v[214:217], v[76:79]
	v_mfma_f32_16x16x32_bf16 v[120:123], v[166:169], v[182:185], v[120:123]
	v_mfma_f32_16x16x32_bf16 v[112:115], v[174:177], v[182:185], v[112:115]
	v_mfma_f32_16x16x32_bf16 v[104:107], v[166:169], v[190:193], v[104:107]
	v_mfma_f32_16x16x32_bf16 v[96:99], v[174:177], v[190:193], v[96:99]
	v_mfma_f32_16x16x32_bf16 v[88:91], v[166:169], v[198:201], v[88:91]
	v_mfma_f32_16x16x32_bf16 v[80:83], v[174:177], v[198:201], v[80:83]
	v_mfma_f32_16x16x32_bf16 v[72:75], v[166:169], v[210:213], v[72:75]
	v_mfma_f32_16x16x32_bf16 v[68:71], v[174:177], v[210:213], v[68:71]
	v_mfma_f32_16x16x32_bf16 v[120:123], v[170:173], v[186:189], v[120:123]
	v_mfma_f32_16x16x32_bf16 v[112:115], v[178:181], v[186:189], v[112:115]
	v_mfma_f32_16x16x32_bf16 v[104:107], v[170:173], v[194:197], v[104:107]
	v_mfma_f32_16x16x32_bf16 v[96:99], v[178:181], v[194:197], v[96:99]
	v_mfma_f32_16x16x32_bf16 v[88:91], v[170:173], v[202:205], v[88:91]
	v_mfma_f32_16x16x32_bf16 v[80:83], v[178:181], v[202:205], v[80:83]
	v_mfma_f32_16x16x32_bf16 v[72:75], v[170:173], v[214:217], v[72:75]
	v_mfma_f32_16x16x32_bf16 v[68:71], v[178:181], v[214:217], v[68:71]
	s_barrier
	s_setprio 0
	s_add_i32 s48, s33, s29
	s_mov_b32 m0, s48
	s_nop 0
	global_load_lds_dwordx4 v134, s[88:89]
	s_add_i32 m0, s48, 0x2000
	s_add_u32 s78, s88, 0x80000
	s_addc_u32 s79, s89, 0
	s_add_i32 s48, s96, s29
	global_load_lds_dwordx4 v138, s[88:89]
	s_mov_b32 m0, s48
	s_nop 0
	global_load_lds_dwordx4 v134, s[78:79]
	s_add_i32 m0, s48, 0x2000
	s_nop 0
	global_load_lds_dwordx4 v138, s[78:79]
	s_mov_b32 m0, s35
	s_nop 0
	global_load_lds_dwordx4 v132, s[90:91]
	s_mov_b32 m0, s60
	s_nop 0
	global_load_lds_dwordx4 v136, s[90:91]
	ds_read_b128 v[182:185], v141 offset:16384
	ds_read_b128 v[186:189], v141 offset:17408
	ds_read_b128 v[190:193], v141 offset:18432
	ds_read_b128 v[194:197], v141 offset:19456
	ds_read_b128 v[198:201], v141 offset:20480
	ds_read_b128 v[202:205], v141 offset:21504
	ds_read_b128 v[210:213], v141 offset:22528
	ds_read_b128 v[214:217], v141 offset:23552
	s_waitcnt vmcnt(8)
	s_waitcnt lgkmcnt(0)
	s_setprio 1
	s_barrier
	v_mfma_f32_16x16x32_bf16 v[64:67], v[150:153], v[182:185], v[64:67]
	v_mfma_f32_16x16x32_bf16 v[60:63], v[158:161], v[182:185], v[60:63]
	v_mfma_f32_16x16x32_bf16 v[52:55], v[150:153], v[190:193], v[52:55]
	v_mfma_f32_16x16x32_bf16 v[44:47], v[158:161], v[190:193], v[44:47]
	v_mfma_f32_16x16x32_bf16 v[36:39], v[150:153], v[198:201], v[36:39]
	v_mfma_f32_16x16x32_bf16 v[28:31], v[158:161], v[198:201], v[28:31]
	v_mfma_f32_16x16x32_bf16 v[20:23], v[150:153], v[210:213], v[20:23]
	v_mfma_f32_16x16x32_bf16 v[12:15], v[158:161], v[210:213], v[12:15]
	v_mfma_f32_16x16x32_bf16 v[64:67], v[154:157], v[186:189], v[64:67]
	v_mfma_f32_16x16x32_bf16 v[60:63], v[162:165], v[186:189], v[60:63]
	v_mfma_f32_16x16x32_bf16 v[52:55], v[154:157], v[194:197], v[52:55]
	v_mfma_f32_16x16x32_bf16 v[44:47], v[162:165], v[194:197], v[44:47]
	v_mfma_f32_16x16x32_bf16 v[36:39], v[154:157], v[202:205], v[36:39]
	v_mfma_f32_16x16x32_bf16 v[28:31], v[162:165], v[202:205], v[28:31]
	v_mfma_f32_16x16x32_bf16 v[20:23], v[154:157], v[214:217], v[20:23]
	v_mfma_f32_16x16x32_bf16 v[12:15], v[162:165], v[214:217], v[12:15]
	v_mfma_f32_16x16x32_bf16 v[56:59], v[166:169], v[182:185], v[56:59]
	v_mfma_f32_16x16x32_bf16 v[48:51], v[174:177], v[182:185], v[48:51]
	v_mfma_f32_16x16x32_bf16 v[40:43], v[166:169], v[190:193], v[40:43]
	v_mfma_f32_16x16x32_bf16 v[32:35], v[174:177], v[190:193], v[32:35]
	v_mfma_f32_16x16x32_bf16 v[24:27], v[166:169], v[198:201], v[24:27]
	v_mfma_f32_16x16x32_bf16 v[16:19], v[174:177], v[198:201], v[16:19]
	v_mfma_f32_16x16x32_bf16 v[8:11], v[166:169], v[210:213], v[8:11]
	v_mfma_f32_16x16x32_bf16 v[4:7], v[174:177], v[210:213], v[4:7]
	v_mfma_f32_16x16x32_bf16 v[56:59], v[170:173], v[186:189], v[56:59]
	v_mfma_f32_16x16x32_bf16 v[48:51], v[178:181], v[186:189], v[48:51]
	v_mfma_f32_16x16x32_bf16 v[40:43], v[170:173], v[194:197], v[40:43]
	v_mfma_f32_16x16x32_bf16 v[32:35], v[178:181], v[194:197], v[32:35]
	v_mfma_f32_16x16x32_bf16 v[24:27], v[170:173], v[202:205], v[24:27]
	v_mfma_f32_16x16x32_bf16 v[16:19], v[178:181], v[202:205], v[16:19]
	v_mfma_f32_16x16x32_bf16 v[8:11], v[170:173], v[214:217], v[8:11]
	v_mfma_f32_16x16x32_bf16 v[4:7], v[178:181], v[214:217], v[4:7]
	s_barrier
	s_setprio 0
	s_add_u32 s78, s90, 0x80000
	s_addc_u32 s79, s91, 0
	s_mov_b32 m0, s61
	s_nop 0
	global_load_lds_dwordx4 v132, s[78:79]
	s_mov_b32 m0, s62
	s_nop 0
	global_load_lds_dwordx4 v136, s[78:79]
	s_add_i32 s97, 0, 0x18000
	s_add_i32 s48, 0, 0x1c000
	ds_read_b128 v[150:153], v248
	ds_read_b128 v[154:157], v248 offset:1024
	ds_read_b128 v[158:161], v248 offset:2048
	ds_read_b128 v[162:165], v248 offset:3072
	ds_read_b128 v[166:169], v249
	ds_read_b128 v[170:173], v249 offset:1024
	ds_read_b128 v[174:177], v249 offset:2048
	ds_read_b128 v[178:181], v249 offset:3072
	ds_read_b128 v[182:185], v141 offset:32768
	ds_read_b128 v[186:189], v141 offset:33792
	ds_read_b128 v[190:193], v141 offset:34816
	ds_read_b128 v[194:197], v141 offset:35840
	ds_read_b128 v[198:201], v141 offset:36864
	ds_read_b128 v[202:205], v141 offset:37888
	ds_read_b128 v[210:213], v141 offset:38912
	ds_read_b128 v[214:217], v141 offset:39936
	s_waitcnt vmcnt(8)
	s_waitcnt lgkmcnt(0)
	s_setprio 1
	s_barrier
	v_mfma_f32_16x16x32_bf16 v[128:131], v[150:153], v[182:185], v[128:131]
	v_mfma_f32_16x16x32_bf16 v[124:127], v[158:161], v[182:185], v[124:127]
	v_mfma_f32_16x16x32_bf16 v[116:119], v[150:153], v[190:193], v[116:119]
	v_mfma_f32_16x16x32_bf16 v[108:111], v[158:161], v[190:193], v[108:111]
	v_mfma_f32_16x16x32_bf16 v[100:103], v[150:153], v[198:201], v[100:103]
	v_mfma_f32_16x16x32_bf16 v[92:95], v[158:161], v[198:201], v[92:95]
	v_mfma_f32_16x16x32_bf16 v[84:87], v[150:153], v[210:213], v[84:87]
	v_mfma_f32_16x16x32_bf16 v[76:79], v[158:161], v[210:213], v[76:79]
	v_mfma_f32_16x16x32_bf16 v[128:131], v[154:157], v[186:189], v[128:131]
	v_mfma_f32_16x16x32_bf16 v[124:127], v[162:165], v[186:189], v[124:127]
	v_mfma_f32_16x16x32_bf16 v[116:119], v[154:157], v[194:197], v[116:119]
	v_mfma_f32_16x16x32_bf16 v[108:111], v[162:165], v[194:197], v[108:111]
	v_mfma_f32_16x16x32_bf16 v[100:103], v[154:157], v[202:205], v[100:103]
	v_mfma_f32_16x16x32_bf16 v[92:95], v[162:165], v[202:205], v[92:95]
	v_mfma_f32_16x16x32_bf16 v[84:87], v[154:157], v[214:217], v[84:87]
	v_mfma_f32_16x16x32_bf16 v[76:79], v[162:165], v[214:217], v[76:79]
	v_mfma_f32_16x16x32_bf16 v[120:123], v[166:169], v[182:185], v[120:123]
	v_mfma_f32_16x16x32_bf16 v[112:115], v[174:177], v[182:185], v[112:115]
	v_mfma_f32_16x16x32_bf16 v[104:107], v[166:169], v[190:193], v[104:107]
	v_mfma_f32_16x16x32_bf16 v[96:99], v[174:177], v[190:193], v[96:99]
	v_mfma_f32_16x16x32_bf16 v[88:91], v[166:169], v[198:201], v[88:91]
	v_mfma_f32_16x16x32_bf16 v[80:83], v[174:177], v[198:201], v[80:83]
	v_mfma_f32_16x16x32_bf16 v[72:75], v[166:169], v[210:213], v[72:75]
	v_mfma_f32_16x16x32_bf16 v[68:71], v[174:177], v[210:213], v[68:71]
	v_mfma_f32_16x16x32_bf16 v[120:123], v[170:173], v[186:189], v[120:123]
	v_mfma_f32_16x16x32_bf16 v[112:115], v[178:181], v[186:189], v[112:115]
	v_mfma_f32_16x16x32_bf16 v[104:107], v[170:173], v[194:197], v[104:107]
	v_mfma_f32_16x16x32_bf16 v[96:99], v[178:181], v[194:197], v[96:99]
	v_mfma_f32_16x16x32_bf16 v[88:91], v[170:173], v[202:205], v[88:91]
	v_mfma_f32_16x16x32_bf16 v[80:83], v[178:181], v[202:205], v[80:83]
	v_mfma_f32_16x16x32_bf16 v[72:75], v[170:173], v[214:217], v[72:75]
	v_mfma_f32_16x16x32_bf16 v[68:71], v[178:181], v[214:217], v[68:71]
	s_barrier
	s_setprio 0
	s_add_i32 s77, s97, s29
	s_mov_b32 m0, s77
	s_nop 0
	s_add_u32 s98, s88, 0x80
	s_addc_u32 s99, s89, 0
	s_nop 0
	global_load_lds_dwordx4 v134, s[98:99]
	s_add_i32 m0, s77, 0x2000
	s_add_u32 s78, s88, 0x80080
	s_addc_u32 s79, s89, 0
	s_add_i32 s77, s48, s29
	global_load_lds_dwordx4 v138, s[98:99]
	s_mov_b32 m0, s77
	s_nop 0
	global_load_lds_dwordx4 v134, s[78:79]
	s_add_i32 m0, s77, 0x2000
	s_nop 0
	global_load_lds_dwordx4 v138, s[78:79]
	s_mov_b32 m0, s63
	s_nop 0
	s_add_u32 s98, s90, 0x80
	s_addc_u32 s99, s91, 0
	s_nop 0
	global_load_lds_dwordx4 v132, s[98:99]
	s_mov_b32 m0, s64
	s_nop 0
	global_load_lds_dwordx4 v136, s[98:99]
	ds_read_b128 v[182:185], v141 offset:49152
	ds_read_b128 v[186:189], v141 offset:50176
	ds_read_b128 v[190:193], v141 offset:51200
	ds_read_b128 v[194:197], v141 offset:52224
	ds_read_b128 v[198:201], v141 offset:53248
	ds_read_b128 v[202:205], v141 offset:54272
	ds_read_b128 v[210:213], v141 offset:55296
	ds_read_b128 v[214:217], v141 offset:56320
	s_waitcnt vmcnt(8)
	s_waitcnt lgkmcnt(0)
	s_setprio 1
	s_barrier
	v_mfma_f32_16x16x32_bf16 v[64:67], v[150:153], v[182:185], v[64:67]
	v_mfma_f32_16x16x32_bf16 v[60:63], v[158:161], v[182:185], v[60:63]
	v_mfma_f32_16x16x32_bf16 v[52:55], v[150:153], v[190:193], v[52:55]
	v_mfma_f32_16x16x32_bf16 v[44:47], v[158:161], v[190:193], v[44:47]
	v_mfma_f32_16x16x32_bf16 v[36:39], v[150:153], v[198:201], v[36:39]
	v_mfma_f32_16x16x32_bf16 v[28:31], v[158:161], v[198:201], v[28:31]
	v_mfma_f32_16x16x32_bf16 v[20:23], v[150:153], v[210:213], v[20:23]
	v_mfma_f32_16x16x32_bf16 v[12:15], v[158:161], v[210:213], v[12:15]
	v_mfma_f32_16x16x32_bf16 v[64:67], v[154:157], v[186:189], v[64:67]
	v_mfma_f32_16x16x32_bf16 v[60:63], v[162:165], v[186:189], v[60:63]
	v_mfma_f32_16x16x32_bf16 v[52:55], v[154:157], v[194:197], v[52:55]
	v_mfma_f32_16x16x32_bf16 v[44:47], v[162:165], v[194:197], v[44:47]
	v_mfma_f32_16x16x32_bf16 v[36:39], v[154:157], v[202:205], v[36:39]
	v_mfma_f32_16x16x32_bf16 v[28:31], v[162:165], v[202:205], v[28:31]
	v_mfma_f32_16x16x32_bf16 v[20:23], v[154:157], v[214:217], v[20:23]
	v_mfma_f32_16x16x32_bf16 v[12:15], v[162:165], v[214:217], v[12:15]
	v_mfma_f32_16x16x32_bf16 v[56:59], v[166:169], v[182:185], v[56:59]
	v_mfma_f32_16x16x32_bf16 v[48:51], v[174:177], v[182:185], v[48:51]
	v_mfma_f32_16x16x32_bf16 v[40:43], v[166:169], v[190:193], v[40:43]
	v_mfma_f32_16x16x32_bf16 v[32:35], v[174:177], v[190:193], v[32:35]
	v_mfma_f32_16x16x32_bf16 v[24:27], v[166:169], v[198:201], v[24:27]
	v_mfma_f32_16x16x32_bf16 v[16:19], v[174:177], v[198:201], v[16:19]
	v_mfma_f32_16x16x32_bf16 v[8:11], v[166:169], v[210:213], v[8:11]
	v_mfma_f32_16x16x32_bf16 v[4:7], v[174:177], v[210:213], v[4:7]
	v_mfma_f32_16x16x32_bf16 v[56:59], v[170:173], v[186:189], v[56:59]
	v_mfma_f32_16x16x32_bf16 v[48:51], v[178:181], v[186:189], v[48:51]
	v_mfma_f32_16x16x32_bf16 v[40:43], v[170:173], v[194:197], v[40:43]
	v_mfma_f32_16x16x32_bf16 v[32:35], v[178:181], v[194:197], v[32:35]
	v_mfma_f32_16x16x32_bf16 v[24:27], v[170:173], v[202:205], v[24:27]
	v_mfma_f32_16x16x32_bf16 v[16:19], v[178:181], v[202:205], v[16:19]
	v_mfma_f32_16x16x32_bf16 v[8:11], v[170:173], v[214:217], v[8:11]
	v_mfma_f32_16x16x32_bf16 v[4:7], v[178:181], v[214:217], v[4:7]
	s_barrier
	s_setprio 0
	s_add_u32 s0, s0, 0x100
	s_addc_u32 s1, s1, 0
	s_add_u32 s56, s56, 0x100
	s_addc_u32 s57, s57, 0
	s_cmp_ge_i32 s76, s55
	s_mov_b32 s88, s76
	s_cbranch_scc0 .LBB0_246
	s_and_b64 vcc, exec, s[58:59]
	s_cbranch_vccz .LBB0_249
	s_barrier
	s_setprio 2

.LBB0_286:
	s_setprio 0
	s_waitcnt vmcnt(0)
	s_barrier
	s_waitcnt vmcnt(0)
	s_waitcnt vmcnt(0)
	s_barrier
	s_mov_b64 s[0:1], exec
	v_readlane_b32 s12, v253, 3
	v_readlane_b32 s13, v253, 4
	s_and_b64 s[12:13], s[0:1], s[12:13]
	s_mov_b64 exec, s[12:13]
	s_cbranch_execz .LBB0_338
	v_readlane_b32 s9, v252, 45
	s_waitcnt vmcnt(0) expcnt(0) lgkmcnt(0)
	s_nop 0
	v_mov_b32_e32 v1, s9
	ds_read_b32 v4, v1
	v_readlane_b32 s9, v252, 46
	s_waitcnt lgkmcnt(0)
	v_cmp_ne_u32_e32 vcc, 0, v4
	v_mov_b32_e32 v1, s9
	ds_read_b32 v2, v1
	s_cbranch_vccnz .LBB0_302
	v_readlane_b32 s16, v253, 1
	v_readlane_b32 s17, v253, 2
	s_load_dwordx2 s[12:13], s[16:17], 0x4
	v_readlane_b32 s9, v253, 0
	s_waitcnt lgkmcnt(0)
	s_mul_i32 s9, s12, s9
	s_mul_i32 s9, s9, s13
	s_mov_b32 s12, 1
	s_branch .LBB0_290

.LBB0_521:
	s_add_i32 s55, s54, 2
	s_add_u32 s56, s74, 0xfff80080
	s_addc_u32 s57, s75, -1
	s_add_i32 m0, s17, 0xc000
	s_add_i32 s76, s17, 0xe000
	global_load_lds_dwordx4 v138, s[74:75]
	s_mov_b32 m0, s76
	s_cmp_eq_u32 s9, s54
	global_load_lds_dwordx4 v140, s[74:75]
	s_cselect_b32 s87, s69, s57
	s_cselect_b32 s86, s68, s56
	s_cselect_b32 s85, s73, s35
	s_cselect_b32 s84, s72, s23
	ds_read_b128 v[146:149], v246
	ds_read_b128 v[150:153], v246 offset:1024
	ds_read_b128 v[154:157], v246 offset:2048
	ds_read_b128 v[158:161], v246 offset:3072
	ds_read_b128 v[162:165], v247
	ds_read_b128 v[166:169], v247 offset:1024
	ds_read_b128 v[170:173], v247 offset:2048
	ds_read_b128 v[174:177], v247 offset:3072
	ds_read_b128 v[178:181], v144
	ds_read_b128 v[182:185], v144 offset:1024
	ds_read_b128 v[186:189], v144 offset:2048
	ds_read_b128 v[190:193], v144 offset:3072
	ds_read_b128 v[194:197], v144 offset:4096
	ds_read_b128 v[198:201], v144 offset:5120
	ds_read_b128 v[202:205], v144 offset:6144
	ds_read_b128 v[210:213], v144 offset:7168
	s_waitcnt vmcnt(8)
	s_waitcnt lgkmcnt(0)
	s_setprio 1
	s_barrier
	v_mfma_f32_16x16x32_bf16 v[128:131], v[146:149], v[178:181], v[128:131]
	v_mfma_f32_16x16x32_bf16 v[124:127], v[154:157], v[178:181], v[124:127]
	v_mfma_f32_16x16x32_bf16 v[120:123], v[146:149], v[186:189], v[120:123]
	v_mfma_f32_16x16x32_bf16 v[116:119], v[154:157], v[186:189], v[116:119]
	v_mfma_f32_16x16x32_bf16 v[104:107], v[146:149], v[194:197], v[104:107]
	v_mfma_f32_16x16x32_bf16 v[100:103], v[154:157], v[194:197], v[100:103]
	v_mfma_f32_16x16x32_bf16 v[88:91], v[146:149], v[202:205], v[88:91]
	v_mfma_f32_16x16x32_bf16 v[84:87], v[154:157], v[202:205], v[84:87]
	v_mfma_f32_16x16x32_bf16 v[128:131], v[150:153], v[182:185], v[128:131]
	v_mfma_f32_16x16x32_bf16 v[124:127], v[158:161], v[182:185], v[124:127]
	v_mfma_f32_16x16x32_bf16 v[120:123], v[150:153], v[190:193], v[120:123]
	v_mfma_f32_16x16x32_bf16 v[116:119], v[158:161], v[190:193], v[116:119]
	v_mfma_f32_16x16x32_bf16 v[104:107], v[150:153], v[198:201], v[104:107]
	v_mfma_f32_16x16x32_bf16 v[100:103], v[158:161], v[198:201], v[100:103]
	v_mfma_f32_16x16x32_bf16 v[88:91], v[150:153], v[210:213], v[88:91]
	v_mfma_f32_16x16x32_bf16 v[84:87], v[158:161], v[210:213], v[84:87]
	v_mfma_f32_16x16x32_bf16 v[112:115], v[162:165], v[178:181], v[112:115]
	v_mfma_f32_16x16x32_bf16 v[108:111], v[170:173], v[178:181], v[108:111]
	v_mfma_f32_16x16x32_bf16 v[96:99], v[162:165], v[186:189], v[96:99]
	v_mfma_f32_16x16x32_bf16 v[92:95], v[170:173], v[186:189], v[92:95]
	v_mfma_f32_16x16x32_bf16 v[80:83], v[162:165], v[194:197], v[80:83]
	v_mfma_f32_16x16x32_bf16 v[76:79], v[170:173], v[194:197], v[76:79]
	v_mfma_f32_16x16x32_bf16 v[72:75], v[162:165], v[202:205], v[72:75]
	v_mfma_f32_16x16x32_bf16 v[68:71], v[170:173], v[202:205], v[68:71]
	v_mfma_f32_16x16x32_bf16 v[112:115], v[166:169], v[182:185], v[112:115]
	v_mfma_f32_16x16x32_bf16 v[108:111], v[174:177], v[182:185], v[108:111]
	v_mfma_f32_16x16x32_bf16 v[96:99], v[166:169], v[190:193], v[96:99]
	v_mfma_f32_16x16x32_bf16 v[92:95], v[174:177], v[190:193], v[92:95]
	v_mfma_f32_16x16x32_bf16 v[80:83], v[166:169], v[198:201], v[80:83]
	v_mfma_f32_16x16x32_bf16 v[76:79], v[174:177], v[198:201], v[76:79]
	v_mfma_f32_16x16x32_bf16 v[72:75], v[166:169], v[210:213], v[72:75]
	v_mfma_f32_16x16x32_bf16 v[68:71], v[174:177], v[210:213], v[68:71]
	s_barrier
	s_setprio 0
	s_add_i32 s54, s33, s16
	s_mov_b32 m0, s54
	s_nop 0
	global_load_lds_dwordx4 v2, s[84:85]
	s_add_i32 m0, s54, 0x2000
	s_add_u32 s56, s84, 0x80000
	s_addc_u32 s57, s85, 0
	s_add_i32 s54, s96, s16
	global_load_lds_dwordx4 v136, s[84:85]
	s_mov_b32 m0, s54
	s_nop 0
	global_load_lds_dwordx4 v2, s[56:57]
	s_add_i32 m0, s54, 0x2000
	s_nop 0
	global_load_lds_dwordx4 v136, s[56:57]
	s_mov_b32 m0, s17
	s_nop 0
	global_load_lds_dwordx4 v132, s[86:87]
	s_mov_b32 m0, s29
	s_nop 0
	global_load_lds_dwordx4 v134, s[86:87]
	ds_read_b128 v[178:181], v144 offset:16384
	ds_read_b128 v[182:185], v144 offset:17408
	ds_read_b128 v[186:189], v144 offset:18432
	ds_read_b128 v[190:193], v144 offset:19456
	ds_read_b128 v[194:197], v144 offset:20480
	ds_read_b128 v[198:201], v144 offset:21504
	ds_read_b128 v[202:205], v144 offset:22528
	ds_read_b128 v[210:213], v144 offset:23552
	s_waitcnt vmcnt(8)
	s_waitcnt lgkmcnt(0)
	s_setprio 1
	s_barrier
	v_mfma_f32_16x16x32_bf16 v[64:67], v[146:149], v[178:181], v[64:67]
	v_mfma_f32_16x16x32_bf16 v[60:63], v[154:157], v[178:181], v[60:63]
	v_mfma_f32_16x16x32_bf16 v[56:59], v[146:149], v[186:189], v[56:59]
	v_mfma_f32_16x16x32_bf16 v[52:55], v[154:157], v[186:189], v[52:55]
	v_mfma_f32_16x16x32_bf16 v[40:43], v[146:149], v[194:197], v[40:43]
	v_mfma_f32_16x16x32_bf16 v[36:39], v[154:157], v[194:197], v[36:39]
	v_mfma_f32_16x16x32_bf16 v[24:27], v[146:149], v[202:205], v[24:27]
	v_mfma_f32_16x16x32_bf16 v[20:23], v[154:157], v[202:205], v[20:23]
	v_mfma_f32_16x16x32_bf16 v[64:67], v[150:153], v[182:185], v[64:67]
	v_mfma_f32_16x16x32_bf16 v[60:63], v[158:161], v[182:185], v[60:63]
	v_mfma_f32_16x16x32_bf16 v[56:59], v[150:153], v[190:193], v[56:59]
	v_mfma_f32_16x16x32_bf16 v[52:55], v[158:161], v[190:193], v[52:55]
	v_mfma_f32_16x16x32_bf16 v[40:43], v[150:153], v[198:201], v[40:43]
	v_mfma_f32_16x16x32_bf16 v[36:39], v[158:161], v[198:201], v[36:39]
	v_mfma_f32_16x16x32_bf16 v[24:27], v[150:153], v[210:213], v[24:27]
	v_mfma_f32_16x16x32_bf16 v[20:23], v[158:161], v[210:213], v[20:23]
	v_mfma_f32_16x16x32_bf16 v[48:51], v[162:165], v[178:181], v[48:51]
	v_mfma_f32_16x16x32_bf16 v[44:47], v[170:173], v[178:181], v[44:47]
	v_mfma_f32_16x16x32_bf16 v[32:35], v[162:165], v[186:189], v[32:35]
	v_mfma_f32_16x16x32_bf16 v[28:31], v[170:173], v[186:189], v[28:31]
	v_mfma_f32_16x16x32_bf16 v[16:19], v[162:165], v[194:197], v[16:19]
	v_mfma_f32_16x16x32_bf16 v[12:15], v[170:173], v[194:197], v[12:15]
	v_mfma_f32_16x16x32_bf16 v[8:11], v[162:165], v[202:205], v[8:11]
	v_mfma_f32_16x16x32_bf16 v[4:7], v[170:173], v[202:205], v[4:7]
	v_mfma_f32_16x16x32_bf16 v[48:51], v[166:169], v[182:185], v[48:51]
	v_mfma_f32_16x16x32_bf16 v[44:47], v[174:177], v[182:185], v[44:47]
	v_mfma_f32_16x16x32_bf16 v[32:35], v[166:169], v[190:193], v[32:35]
	v_mfma_f32_16x16x32_bf16 v[28:31], v[174:177], v[190:193], v[28:31]
	v_mfma_f32_16x16x32_bf16 v[16:19], v[166:169], v[198:201], v[16:19]
	v_mfma_f32_16x16x32_bf16 v[12:15], v[174:177], v[198:201], v[12:15]
	v_mfma_f32_16x16x32_bf16 v[8:11], v[166:169], v[210:213], v[8:11]
	v_mfma_f32_16x16x32_bf16 v[4:7], v[174:177], v[210:213], v[4:7]
	s_barrier
	s_setprio 0
	s_add_u32 s56, s86, 0x80000
	s_addc_u32 s57, s87, 0
	s_mov_b32 m0, s60
	s_nop 0
	global_load_lds_dwordx4 v132, s[56:57]
	s_mov_b32 m0, s61
	s_nop 0
	global_load_lds_dwordx4 v134, s[56:57]
	ds_read_b128 v[146:149], v248
	ds_read_b128 v[150:153], v248 offset:1024
	ds_read_b128 v[154:157], v248 offset:2048
	ds_read_b128 v[158:161], v248 offset:3072
	ds_read_b128 v[162:165], v249
	ds_read_b128 v[166:169], v249 offset:1024
	ds_read_b128 v[170:173], v249 offset:2048
	ds_read_b128 v[174:177], v249 offset:3072
	ds_read_b128 v[178:181], v144 offset:32768
	ds_read_b128 v[182:185], v144 offset:33792
	ds_read_b128 v[186:189], v144 offset:34816
	ds_read_b128 v[190:193], v144 offset:35840
	ds_read_b128 v[194:197], v144 offset:36864
	ds_read_b128 v[198:201], v144 offset:37888
	ds_read_b128 v[202:205], v144 offset:38912
	ds_read_b128 v[210:213], v144 offset:39936
	s_waitcnt vmcnt(8)
	s_waitcnt lgkmcnt(0)
	s_setprio 1
	s_barrier
	v_mfma_f32_16x16x32_bf16 v[128:131], v[146:149], v[178:181], v[128:131]
	v_mfma_f32_16x16x32_bf16 v[124:127], v[154:157], v[178:181], v[124:127]
	v_mfma_f32_16x16x32_bf16 v[120:123], v[146:149], v[186:189], v[120:123]
	v_mfma_f32_16x16x32_bf16 v[116:119], v[154:157], v[186:189], v[116:119]
	v_mfma_f32_16x16x32_bf16 v[104:107], v[146:149], v[194:197], v[104:107]
	v_mfma_f32_16x16x32_bf16 v[100:103], v[154:157], v[194:197], v[100:103]
	v_mfma_f32_16x16x32_bf16 v[88:91], v[146:149], v[202:205], v[88:91]
	v_mfma_f32_16x16x32_bf16 v[84:87], v[154:157], v[202:205], v[84:87]
	v_mfma_f32_16x16x32_bf16 v[128:131], v[150:153], v[182:185], v[128:131]
	v_mfma_f32_16x16x32_bf16 v[124:127], v[158:161], v[182:185], v[124:127]
	v_mfma_f32_16x16x32_bf16 v[120:123], v[150:153], v[190:193], v[120:123]
	v_mfma_f32_16x16x32_bf16 v[116:119], v[158:161], v[190:193], v[116:119]
	v_mfma_f32_16x16x32_bf16 v[104:107], v[150:153], v[198:201], v[104:107]
	v_mfma_f32_16x16x32_bf16 v[100:103], v[158:161], v[198:201], v[100:103]
	v_mfma_f32_16x16x32_bf16 v[88:91], v[150:153], v[210:213], v[88:91]
	v_mfma_f32_16x16x32_bf16 v[84:87], v[158:161], v[210:213], v[84:87]
	v_mfma_f32_16x16x32_bf16 v[112:115], v[162:165], v[178:181], v[112:115]
	v_mfma_f32_16x16x32_bf16 v[108:111], v[170:173], v[178:181], v[108:111]
	v_mfma_f32_16x16x32_bf16 v[96:99], v[162:165], v[186:189], v[96:99]
	v_mfma_f32_16x16x32_bf16 v[92:95], v[170:173], v[186:189], v[92:95]
	v_mfma_f32_16x16x32_bf16 v[80:83], v[162:165], v[194:197], v[80:83]
	v_mfma_f32_16x16x32_bf16 v[76:79], v[170:173], v[194:197], v[76:79]
	v_mfma_f32_16x16x32_bf16 v[72:75], v[162:165], v[202:205], v[72:75]
	v_mfma_f32_16x16x32_bf16 v[68:71], v[170:173], v[202:205], v[68:71]
	v_mfma_f32_16x16x32_bf16 v[112:115], v[166:169], v[182:185], v[112:115]
	v_mfma_f32_16x16x32_bf16 v[108:111], v[174:177], v[182:185], v[108:111]
	v_mfma_f32_16x16x32_bf16 v[96:99], v[166:169], v[190:193], v[96:99]
	v_mfma_f32_16x16x32_bf16 v[92:95], v[174:177], v[190:193], v[92:95]
	v_mfma_f32_16x16x32_bf16 v[80:83], v[166:169], v[198:201], v[80:83]
	v_mfma_f32_16x16x32_bf16 v[76:79], v[174:177], v[198:201], v[76:79]
	v_mfma_f32_16x16x32_bf16 v[72:75], v[166:169], v[210:213], v[72:75]
	v_mfma_f32_16x16x32_bf16 v[68:71], v[174:177], v[210:213], v[68:71]
	s_barrier
	s_setprio 0
	s_add_i32 s54, s97, s16
	s_mov_b32 m0, s54
	s_nop 0
	s_add_u32 s98, s84, 0x80
	s_addc_u32 s99, s85, 0
	s_nop 0
	global_load_lds_dwordx4 v2, s[98:99]
	s_add_i32 m0, s54, 0x2000
	s_add_u32 s56, s84, 0x80080
	s_addc_u32 s57, s85, 0
	s_add_i32 s54, s48, s16
	global_load_lds_dwordx4 v136, s[98:99]
	s_mov_b32 m0, s54
	s_nop 0
	global_load_lds_dwordx4 v2, s[56:57]
	s_add_i32 m0, s54, 0x2000
	s_nop 0
	global_load_lds_dwordx4 v136, s[56:57]
	s_mov_b32 m0, s62
	s_nop 0
	s_add_u32 s98, s86, 0x80
	s_addc_u32 s99, s87, 0
	s_nop 0
	global_load_lds_dwordx4 v132, s[98:99]
	s_mov_b32 m0, s63
	s_nop 0
	global_load_lds_dwordx4 v134, s[98:99]
	ds_read_b128 v[178:181], v144 offset:49152
	ds_read_b128 v[182:185], v144 offset:50176
	ds_read_b128 v[186:189], v144 offset:51200
	ds_read_b128 v[190:193], v144 offset:52224
	ds_read_b128 v[194:197], v144 offset:53248
	ds_read_b128 v[198:201], v144 offset:54272
	ds_read_b128 v[202:205], v144 offset:55296
	ds_read_b128 v[210:213], v144 offset:56320
	s_waitcnt vmcnt(8)
	s_waitcnt lgkmcnt(0)
	s_setprio 1
	s_barrier
	v_mfma_f32_16x16x32_bf16 v[64:67], v[146:149], v[178:181], v[64:67]
	v_mfma_f32_16x16x32_bf16 v[60:63], v[154:157], v[178:181], v[60:63]
	v_mfma_f32_16x16x32_bf16 v[56:59], v[146:149], v[186:189], v[56:59]
	v_mfma_f32_16x16x32_bf16 v[52:55], v[154:157], v[186:189], v[52:55]
	v_mfma_f32_16x16x32_bf16 v[40:43], v[146:149], v[194:197], v[40:43]
	v_mfma_f32_16x16x32_bf16 v[36:39], v[154:157], v[194:197], v[36:39]
	v_mfma_f32_16x16x32_bf16 v[24:27], v[146:149], v[202:205], v[24:27]
	v_mfma_f32_16x16x32_bf16 v[20:23], v[154:157], v[202:205], v[20:23]
	v_mfma_f32_16x16x32_bf16 v[64:67], v[150:153], v[182:185], v[64:67]
	v_mfma_f32_16x16x32_bf16 v[60:63], v[158:161], v[182:185], v[60:63]
	v_mfma_f32_16x16x32_bf16 v[56:59], v[150:153], v[190:193], v[56:59]
	v_mfma_f32_16x16x32_bf16 v[52:55], v[158:161], v[190:193], v[52:55]
	v_mfma_f32_16x16x32_bf16 v[40:43], v[150:153], v[198:201], v[40:43]
	v_mfma_f32_16x16x32_bf16 v[36:39], v[158:161], v[198:201], v[36:39]
	v_mfma_f32_16x16x32_bf16 v[24:27], v[150:153], v[210:213], v[24:27]
	v_mfma_f32_16x16x32_bf16 v[20:23], v[158:161], v[210:213], v[20:23]
	v_mfma_f32_16x16x32_bf16 v[48:51], v[162:165], v[178:181], v[48:51]
	v_mfma_f32_16x16x32_bf16 v[44:47], v[170:173], v[178:181], v[44:47]
	v_mfma_f32_16x16x32_bf16 v[32:35], v[162:165], v[186:189], v[32:35]
	v_mfma_f32_16x16x32_bf16 v[28:31], v[170:173], v[186:189], v[28:31]
	v_mfma_f32_16x16x32_bf16 v[16:19], v[162:165], v[194:197], v[16:19]
	v_mfma_f32_16x16x32_bf16 v[12:15], v[170:173], v[194:197], v[12:15]
	v_mfma_f32_16x16x32_bf16 v[8:11], v[162:165], v[202:205], v[8:11]
	v_mfma_f32_16x16x32_bf16 v[4:7], v[170:173], v[202:205], v[4:7]
	v_mfma_f32_16x16x32_bf16 v[48:51], v[166:169], v[182:185], v[48:51]
	v_mfma_f32_16x16x32_bf16 v[44:47], v[174:177], v[182:185], v[44:47]
	v_mfma_f32_16x16x32_bf16 v[32:35], v[166:169], v[190:193], v[32:35]
	v_mfma_f32_16x16x32_bf16 v[28:31], v[174:177], v[190:193], v[28:31]
	v_mfma_f32_16x16x32_bf16 v[16:19], v[166:169], v[198:201], v[16:19]
	v_mfma_f32_16x16x32_bf16 v[12:15], v[174:177], v[198:201], v[12:15]
	v_mfma_f32_16x16x32_bf16 v[8:11], v[166:169], v[210:213], v[8:11]
	v_mfma_f32_16x16x32_bf16 v[4:7], v[174:177], v[210:213], v[4:7]
	s_barrier
	s_setprio 0
	s_add_u32 s74, s74, 0x100
	s_addc_u32 s75, s75, 0
	s_add_u32 s23, s23, 0x100
	s_addc_u32 s35, s35, 0
	s_cmp_ge_u32 s55, s64
	s_mov_b32 s54, s55
	s_cbranch_scc0 .LBB0_521
	s_and_b64 vcc, exec, s[58:59]
	s_cbranch_vccz .LBB0_524
	s_barrier
	s_setprio 2

.LBB0_527:
	s_setprio 0
	v_mov_b32_e32 v1, v0
	s_waitcnt vmcnt(0)
	s_barrier
	s_waitcnt vmcnt(0)
	s_lshl_b32 s78, s49, 11
	v_readfirstlane_b32 s23, v1
	v_readlane_b32 s16, v252, 52
	s_mov_b32 s79, s65
	s_cmp_gt_u32 s23, 63
	s_mov_b64 s[0:1], -1
	v_readlane_b32 s17, v252, 53
	s_waitcnt vmcnt(0)
	s_barrier
	s_cbranch_scc0 .LBB0_557
	s_mov_b64 s[50:51], s[78:79]
	s_lshl_b64 s[12:13], s[78:79], 2
	v_readlane_b32 s72, v253, 7
	v_readlane_b32 s74, v253, 9
	v_readlane_b32 s75, v253, 10
	s_add_u32 s0, s74, s12
	v_readlane_b32 s76, v253, 11
	s_addc_u32 s1, s75, s13
	v_readlane_b32 s77, v253, 12
	s_add_u32 s36, s76, s12
	s_movk_i32 s9, 0x1840
	s_addc_u32 s37, s77, s13
	s_mul_i32 s64, s49, 3
	v_cmp_gt_i32_e32 vcc, s9, v1
	v_lshl_add_u32 v2, v1, 2, 0
	v_readlane_b32 s73, v253, 8
	v_readlane_b32 s78, v253, 13
	v_readlane_b32 s79, v253, 14
	v_readlane_b32 s80, v253, 15
	v_readlane_b32 s81, v253, 16
	v_readlane_b32 s82, v253, 17
	v_readlane_b32 s83, v253, 18
	v_readlane_b32 s84, v253, 19
	v_readlane_b32 s85, v253, 20
	v_readlane_b32 s86, v253, 21
	v_readlane_b32 s87, v253, 22
	s_movk_i32 s29, 0x4000
	s_mov_b64 s[78:79], s[50:51]
	s_mul_i32 s12, s64, 0xc000
	s_add_u32 s12, s16, s12
	s_addc_u32 s13, s17, 0
	s_add_u32 s74, s12, 0x4000
	s_addc_u32 s75, s13, 0
	s_add_u32 s76, s12, 0x8000
	s_addc_u32 s77, s13, 0
	s_add_u32 s80, s12, 0x6000
	s_addc_u32 s81, s13, 0
	s_mov_b64 s[68:69], exec
	v_subrev_u32_e32 v4, 64, v1
	v_add_u32_e32 v5, 0xffffff00, v2
	v_add_u32_e32 v6, 0xc000, v5
	s_mov_b32 s9, 0xc000
	v_mov_b32_e32 v8, v4
	v_lshrrev_b32_e32 v9, 11, v8
	v_and_b32_e32 v8, 0x7ff, v8
	v_lshlrev_b32_e32 v8, 2, v8
	v_mad_u32_u24 v9, v9, s9, v8
	global_load_dword v10, v9, s[74:75]
	global_load_dword v11, v8, s[0:1]
	global_load_dword v12, v8, s[36:37]
	global_load_dword v13, v9, s[76:77]
	global_load_dword v14, v9, s[80:81]
	v_add_u32_e32 v16, 448, v4
	v_lshrrev_b32_e32 v17, 11, v16
	v_and_b32_e32 v16, 0x7ff, v16
	v_lshlrev_b32_e32 v16, 2, v16
	v_mad_u32_u24 v17, v17, s9, v16
	global_load_dword v18, v17, s[74:75]
	global_load_dword v19, v16, s[0:1]
	global_load_dword v20, v16, s[36:37]
	global_load_dword v21, v17, s[76:77]
	global_load_dword v22, v17, s[80:81]
	v_add_u32_e32 v24, 896, v4
	v_lshrrev_b32_e32 v25, 11, v24
	v_and_b32_e32 v24, 0x7ff, v24
	v_lshlrev_b32_e32 v24, 2, v24
	v_mad_u32_u24 v25, v25, s9, v24
	global_load_dword v26, v25, s[74:75]
	global_load_dword v27, v24, s[0:1]
	global_load_dword v28, v24, s[36:37]
	global_load_dword v29, v25, s[76:77]
	global_load_dword v30, v25, s[80:81]
	v_add_u32_e32 v32, 1344, v4
	v_lshrrev_b32_e32 v33, 11, v32
	v_and_b32_e32 v32, 0x7ff, v32
	v_lshlrev_b32_e32 v32, 2, v32
	v_mad_u32_u24 v33, v33, s9, v32
	global_load_dword v34, v33, s[74:75]
	global_load_dword v35, v32, s[0:1]
	global_load_dword v36, v32, s[36:37]
	global_load_dword v37, v33, s[76:77]
	global_load_dword v38, v33, s[80:81]
	v_add_u32_e32 v40, 1792, v4
	v_lshrrev_b32_e32 v41, 11, v40
	v_and_b32_e32 v40, 0x7ff, v40
	v_lshlrev_b32_e32 v40, 2, v40
	v_mad_u32_u24 v41, v41, s9, v40
	global_load_dword v42, v41, s[74:75]
	global_load_dword v43, v40, s[0:1]
	global_load_dword v44, v40, s[36:37]
	global_load_dword v45, v41, s[76:77]
	global_load_dword v46, v41, s[80:81]
	v_add_u32_e32 v48, 2240, v4
	v_lshrrev_b32_e32 v49, 11, v48
	v_and_b32_e32 v48, 0x7ff, v48
	v_lshlrev_b32_e32 v48, 2, v48
	v_mad_u32_u24 v49, v49, s9, v48
	global_load_dword v50, v49, s[74:75]
	global_load_dword v51, v48, s[0:1]
	global_load_dword v52, v48, s[36:37]
	global_load_dword v53, v49, s[76:77]
	global_load_dword v54, v49, s[80:81]
	v_add_u32_e32 v56, 2688, v4
	v_lshrrev_b32_e32 v57, 11, v56
	v_and_b32_e32 v56, 0x7ff, v56
	v_lshlrev_b32_e32 v56, 2, v56
	v_mad_u32_u24 v57, v57, s9, v56
	global_load_dword v58, v57, s[74:75]
	global_load_dword v59, v56, s[0:1]
	global_load_dword v60, v56, s[36:37]
	global_load_dword v61, v57, s[76:77]
	global_load_dword v62, v57, s[80:81]
	v_add_u32_e32 v64, 3136, v4
	v_lshrrev_b32_e32 v65, 11, v64
	v_and_b32_e32 v64, 0x7ff, v64
	v_lshlrev_b32_e32 v64, 2, v64
	v_mad_u32_u24 v65, v65, s9, v64
	global_load_dword v66, v65, s[74:75]
	global_load_dword v67, v64, s[0:1]
	global_load_dword v68, v64, s[36:37]
	global_load_dword v69, v65, s[76:77]
	global_load_dword v70, v65, s[80:81]
	v_add_u32_e32 v72, 3584, v4
	v_lshrrev_b32_e32 v73, 11, v72
	v_and_b32_e32 v72, 0x7ff, v72
	v_lshlrev_b32_e32 v72, 2, v72
	v_mad_u32_u24 v73, v73, s9, v72
	global_load_dword v74, v73, s[74:75]
	global_load_dword v75, v72, s[0:1]
	global_load_dword v76, v72, s[36:37]
	global_load_dword v77, v73, s[76:77]
	global_load_dword v78, v73, s[80:81]
	v_add_u32_e32 v80, 4032, v4
	v_lshrrev_b32_e32 v81, 11, v80
	v_and_b32_e32 v80, 0x7ff, v80
	v_lshlrev_b32_e32 v80, 2, v80
	v_mad_u32_u24 v81, v81, s9, v80
	global_load_dword v82, v81, s[74:75]
	global_load_dword v83, v80, s[0:1]
	global_load_dword v84, v80, s[36:37]
	global_load_dword v85, v81, s[76:77]
	global_load_dword v86, v81, s[80:81]
	v_add_u32_e32 v88, 4480, v4
	v_lshrrev_b32_e32 v89, 11, v88
	v_and_b32_e32 v88, 0x7ff, v88
	v_lshlrev_b32_e32 v88, 2, v88
	v_mad_u32_u24 v89, v89, s9, v88
	global_load_dword v90, v89, s[74:75]
	global_load_dword v91, v88, s[0:1]
	global_load_dword v92, v88, s[36:37]
	global_load_dword v93, v89, s[76:77]
	global_load_dword v94, v89, s[80:81]
	v_add_u32_e32 v96, 4928, v4
	v_lshrrev_b32_e32 v97, 11, v96
	v_and_b32_e32 v96, 0x7ff, v96
	v_lshlrev_b32_e32 v96, 2, v96
	v_mad_u32_u24 v97, v97, s9, v96
	global_load_dword v98, v97, s[74:75]
	global_load_dword v99, v96, s[0:1]
	global_load_dword v100, v96, s[36:37]
	global_load_dword v101, v97, s[76:77]
	global_load_dword v102, v97, s[80:81]
	s_waitcnt vmcnt(55)
	v_mul_f32_e32 v10, v10, v11
	v_add_f32_e32 v13, 1.0, v13
	v_mul_f32_e32 v13, v12, v13
	ds_write_b32 v5, v10 offset:0
	ds_write_b32 v5, v13 offset:24576
	ds_write_b32 v6, v14 offset:0
	v_add_u32_e32 v104, 5376, v4
	v_lshrrev_b32_e32 v105, 11, v104
	v_and_b32_e32 v104, 0x7ff, v104
	v_lshlrev_b32_e32 v104, 2, v104
	v_mad_u32_u24 v105, v105, s9, v104
	global_load_dword v106, v105, s[74:75]
	global_load_dword v107, v104, s[0:1]
	global_load_dword v108, v104, s[36:37]
	global_load_dword v109, v105, s[76:77]
	global_load_dword v110, v105, s[80:81]
	s_waitcnt vmcnt(55)
	v_mul_f32_e32 v18, v18, v19
	v_add_f32_e32 v21, 1.0, v21
	v_mul_f32_e32 v21, v20, v21
	ds_write_b32 v5, v18 offset:1792
	ds_write_b32 v5, v21 offset:26368
	ds_write_b32 v6, v22 offset:1792
	v_add_u32_e32 v112, 5824, v4
	v_lshrrev_b32_e32 v113, 11, v112
	v_and_b32_e32 v112, 0x7ff, v112
	v_lshlrev_b32_e32 v112, 2, v112
	v_mad_u32_u24 v113, v113, s9, v112
	global_load_dword v114, v113, s[74:75]
	global_load_dword v115, v112, s[0:1]
	global_load_dword v116, v112, s[36:37]
	global_load_dword v117, v113, s[76:77]
	global_load_dword v118, v113, s[80:81]
	s_waitcnt vmcnt(55)
	v_mul_f32_e32 v26, v26, v27
	v_add_f32_e32 v29, 1.0, v29
	v_mul_f32_e32 v29, v28, v29
	ds_write_b32 v5, v26 offset:3584
	ds_write_b32 v5, v29 offset:28160
	ds_write_b32 v6, v30 offset:3584
	s_waitcnt vmcnt(50)
	v_mul_f32_e32 v34, v34, v35
	v_add_f32_e32 v37, 1.0, v37
	v_mul_f32_e32 v37, v36, v37
	ds_write_b32 v5, v34 offset:5376
	ds_write_b32 v5, v37 offset:29952
	ds_write_b32 v6, v38 offset:5376
	s_waitcnt vmcnt(45)
	v_mul_f32_e32 v42, v42, v43
	v_add_f32_e32 v45, 1.0, v45
	v_mul_f32_e32 v45, v44, v45
	ds_write_b32 v5, v42 offset:7168
	ds_write_b32 v5, v45 offset:31744
	ds_write_b32 v6, v46 offset:7168
	s_waitcnt vmcnt(40)
	v_mul_f32_e32 v50, v50, v51
	v_add_f32_e32 v53, 1.0, v53
	v_mul_f32_e32 v53, v52, v53
	ds_write_b32 v5, v50 offset:8960
	ds_write_b32 v5, v53 offset:33536
	ds_write_b32 v6, v54 offset:8960
	s_waitcnt vmcnt(35)
	v_mul_f32_e32 v58, v58, v59
	v_add_f32_e32 v61, 1.0, v61
	v_mul_f32_e32 v61, v60, v61
	ds_write_b32 v5, v58 offset:10752
	ds_write_b32 v5, v61 offset:35328
	ds_write_b32 v6, v62 offset:10752
	s_waitcnt vmcnt(30)
	v_mul_f32_e32 v66, v66, v67
	v_add_f32_e32 v69, 1.0, v69
	v_mul_f32_e32 v69, v68, v69
	ds_write_b32 v5, v66 offset:12544
	ds_write_b32 v5, v69 offset:37120
	ds_write_b32 v6, v70 offset:12544
	s_waitcnt vmcnt(25)
	v_mul_f32_e32 v74, v74, v75
	v_add_f32_e32 v77, 1.0, v77
	v_mul_f32_e32 v77, v76, v77
	ds_write_b32 v5, v74 offset:14336
	ds_write_b32 v5, v77 offset:38912
	ds_write_b32 v6, v78 offset:14336
	s_waitcnt vmcnt(20)
	v_mul_f32_e32 v82, v82, v83
	v_add_f32_e32 v85, 1.0, v85
	v_mul_f32_e32 v85, v84, v85
	ds_write_b32 v5, v82 offset:16128
	ds_write_b32 v5, v85 offset:40704
	ds_write_b32 v6, v86 offset:16128
	s_waitcnt vmcnt(15)
	v_mul_f32_e32 v90, v90, v91
	v_add_f32_e32 v93, 1.0, v93
	v_mul_f32_e32 v93, v92, v93
	ds_write_b32 v5, v90 offset:17920
	ds_write_b32 v5, v93 offset:42496
	ds_write_b32 v6, v94 offset:17920
	s_waitcnt vmcnt(10)
	v_mul_f32_e32 v98, v98, v99
	v_add_f32_e32 v101, 1.0, v101
	v_mul_f32_e32 v101, v100, v101
	ds_write_b32 v5, v98 offset:19712
	ds_write_b32 v5, v101 offset:44288
	ds_write_b32 v6, v102 offset:19712
	s_waitcnt vmcnt(5)
	v_mul_f32_e32 v106, v106, v107
	v_add_f32_e32 v109, 1.0, v109
	v_mul_f32_e32 v109, v108, v109
	ds_write_b32 v5, v106 offset:21504
	ds_write_b32 v5, v109 offset:46080
	ds_write_b32 v6, v110 offset:21504
	s_waitcnt vmcnt(0)
	v_cmp_gt_u32_e32 vcc, 0x140, v4
	s_and_saveexec_b64 s[68:69], vcc
	s_cbranch_execz .Ltb_p4_p13
	v_mul_f32_e32 v114, v114, v115
	v_add_f32_e32 v117, 1.0, v117
	v_mul_f32_e32 v117, v116, v117
	ds_write_b32 v5, v114 offset:23296
	ds_write_b32 v5, v117 offset:47872
	ds_write_b32 v6, v118 offset:23296

.LBB0_694:
	s_add_u32 s57, s88, 0xfff80080
	s_addc_u32 s73, s89, -1
	s_add_i32 m0, s60, 0xc000
	s_add_i32 s75, s60, 0xe000
	global_load_lds_dwordx4 v138, s[88:89]
	s_mov_b32 m0, s75
	s_cmp_eq_u32 s56, 28
	global_load_lds_dwordx4 v140, s[88:89]
	s_cselect_b32 vcc_hi, s16, s73
	s_cselect_b32 vcc_lo, s17, s57
	s_cselect_b32 s91, s50, s55
	s_cselect_b32 s90, s51, s54
	ds_read_b128 v[148:151], v246
	ds_read_b128 v[152:155], v246 offset:1024
	ds_read_b128 v[156:159], v246 offset:2048
	ds_read_b128 v[160:163], v246 offset:3072
	ds_read_b128 v[164:167], v247
	ds_read_b128 v[168:171], v247 offset:1024
	ds_read_b128 v[172:175], v247 offset:2048
	ds_read_b128 v[176:179], v247 offset:3072
	ds_read_b128 v[180:183], v146
	ds_read_b128 v[184:187], v146 offset:1024
	ds_read_b128 v[188:191], v146 offset:2048
	ds_read_b128 v[192:195], v146 offset:3072
	ds_read_b128 v[196:199], v146 offset:4096
	ds_read_b128 v[200:203], v146 offset:5120
	ds_read_b128 v[210:213], v146 offset:6144
	ds_read_b128 v[214:217], v146 offset:7168
	s_waitcnt vmcnt(8)
	s_waitcnt lgkmcnt(0)
	s_setprio 1
	s_barrier
	v_mfma_f32_16x16x32_bf16 v[128:131], v[148:151], v[180:183], v[128:131]
	v_mfma_f32_16x16x32_bf16 v[124:127], v[156:159], v[180:183], v[124:127]
	v_mfma_f32_16x16x32_bf16 v[112:115], v[148:151], v[188:191], v[112:115]
	v_mfma_f32_16x16x32_bf16 v[108:111], v[156:159], v[188:191], v[108:111]
	v_mfma_f32_16x16x32_bf16 v[96:99], v[148:151], v[196:199], v[96:99]
	v_mfma_f32_16x16x32_bf16 v[92:95], v[156:159], v[196:199], v[92:95]
	v_mfma_f32_16x16x32_bf16 v[80:83], v[148:151], v[210:213], v[80:83]
	v_mfma_f32_16x16x32_bf16 v[76:79], v[156:159], v[210:213], v[76:79]
	v_mfma_f32_16x16x32_bf16 v[128:131], v[152:155], v[184:187], v[128:131]
	v_mfma_f32_16x16x32_bf16 v[124:127], v[160:163], v[184:187], v[124:127]
	v_mfma_f32_16x16x32_bf16 v[112:115], v[152:155], v[192:195], v[112:115]
	v_mfma_f32_16x16x32_bf16 v[108:111], v[160:163], v[192:195], v[108:111]
	v_mfma_f32_16x16x32_bf16 v[96:99], v[152:155], v[200:203], v[96:99]
	v_mfma_f32_16x16x32_bf16 v[92:95], v[160:163], v[200:203], v[92:95]
	v_mfma_f32_16x16x32_bf16 v[80:83], v[152:155], v[214:217], v[80:83]
	v_mfma_f32_16x16x32_bf16 v[76:79], v[160:163], v[214:217], v[76:79]
	v_mfma_f32_16x16x32_bf16 v[120:123], v[164:167], v[180:183], v[120:123]
	v_mfma_f32_16x16x32_bf16 v[116:119], v[172:175], v[180:183], v[116:119]
	v_mfma_f32_16x16x32_bf16 v[104:107], v[164:167], v[188:191], v[104:107]
	v_mfma_f32_16x16x32_bf16 v[100:103], v[172:175], v[188:191], v[100:103]
	v_mfma_f32_16x16x32_bf16 v[88:91], v[164:167], v[196:199], v[88:91]
	v_mfma_f32_16x16x32_bf16 v[84:87], v[172:175], v[196:199], v[84:87]
	v_mfma_f32_16x16x32_bf16 v[72:75], v[164:167], v[210:213], v[72:75]
	v_mfma_f32_16x16x32_bf16 v[68:71], v[172:175], v[210:213], v[68:71]
	v_mfma_f32_16x16x32_bf16 v[120:123], v[168:171], v[184:187], v[120:123]
	v_mfma_f32_16x16x32_bf16 v[116:119], v[176:179], v[184:187], v[116:119]
	v_mfma_f32_16x16x32_bf16 v[104:107], v[168:171], v[192:195], v[104:107]
	v_mfma_f32_16x16x32_bf16 v[100:103], v[176:179], v[192:195], v[100:103]
	v_mfma_f32_16x16x32_bf16 v[88:91], v[168:171], v[200:203], v[88:91]
	v_mfma_f32_16x16x32_bf16 v[84:87], v[176:179], v[200:203], v[84:87]
	v_mfma_f32_16x16x32_bf16 v[72:75], v[168:171], v[214:217], v[72:75]
	v_mfma_f32_16x16x32_bf16 v[68:71], v[176:179], v[214:217], v[68:71]
	s_barrier
	s_setprio 0
	s_add_i32 s57, s33, s35
	s_mov_b32 m0, s57
	s_nop 0
	global_load_lds_dwordx4 v2, s[90:91]
	s_add_i32 m0, s57, 0x2000
	s_add_u32 s76, s90, 0x80000
	s_addc_u32 s77, s91, 0
	s_add_i32 s57, s96, s35
	global_load_lds_dwordx4 v132, s[90:91]
	s_mov_b32 m0, s57
	s_nop 0
	global_load_lds_dwordx4 v2, s[76:77]
	s_add_i32 m0, s57, 0x2000
	s_nop 0
	global_load_lds_dwordx4 v132, s[76:77]
	s_mov_b32 m0, s60
	s_nop 0
	global_load_lds_dwordx4 v136, vcc
	s_mov_b32 m0, s61
	s_nop 0
	global_load_lds_dwordx4 v134, vcc
	ds_read_b128 v[180:183], v146 offset:16384
	ds_read_b128 v[184:187], v146 offset:17408
	ds_read_b128 v[188:191], v146 offset:18432
	ds_read_b128 v[192:195], v146 offset:19456
	ds_read_b128 v[196:199], v146 offset:20480
	ds_read_b128 v[200:203], v146 offset:21504
	ds_read_b128 v[210:213], v146 offset:22528
	ds_read_b128 v[214:217], v146 offset:23552
	s_waitcnt vmcnt(8)
	s_waitcnt lgkmcnt(0)
	s_setprio 1
	s_barrier
	v_mfma_f32_16x16x32_bf16 v[64:67], v[148:151], v[180:183], v[64:67]
	v_mfma_f32_16x16x32_bf16 v[60:63], v[156:159], v[180:183], v[60:63]
	v_mfma_f32_16x16x32_bf16 v[48:51], v[148:151], v[188:191], v[48:51]
	v_mfma_f32_16x16x32_bf16 v[44:47], v[156:159], v[188:191], v[44:47]
	v_mfma_f32_16x16x32_bf16 v[32:35], v[148:151], v[196:199], v[32:35]
	v_mfma_f32_16x16x32_bf16 v[28:31], v[156:159], v[196:199], v[28:31]
	v_mfma_f32_16x16x32_bf16 v[16:19], v[148:151], v[210:213], v[16:19]
	v_mfma_f32_16x16x32_bf16 v[12:15], v[156:159], v[210:213], v[12:15]
	v_mfma_f32_16x16x32_bf16 v[64:67], v[152:155], v[184:187], v[64:67]
	v_mfma_f32_16x16x32_bf16 v[60:63], v[160:163], v[184:187], v[60:63]
	v_mfma_f32_16x16x32_bf16 v[48:51], v[152:155], v[192:195], v[48:51]
	v_mfma_f32_16x16x32_bf16 v[44:47], v[160:163], v[192:195], v[44:47]
	v_mfma_f32_16x16x32_bf16 v[32:35], v[152:155], v[200:203], v[32:35]
	v_mfma_f32_16x16x32_bf16 v[28:31], v[160:163], v[200:203], v[28:31]
	v_mfma_f32_16x16x32_bf16 v[16:19], v[152:155], v[214:217], v[16:19]
	v_mfma_f32_16x16x32_bf16 v[12:15], v[160:163], v[214:217], v[12:15]
	v_mfma_f32_16x16x32_bf16 v[56:59], v[164:167], v[180:183], v[56:59]
	v_mfma_f32_16x16x32_bf16 v[52:55], v[172:175], v[180:183], v[52:55]
	v_mfma_f32_16x16x32_bf16 v[40:43], v[164:167], v[188:191], v[40:43]
	v_mfma_f32_16x16x32_bf16 v[36:39], v[172:175], v[188:191], v[36:39]
	v_mfma_f32_16x16x32_bf16 v[24:27], v[164:167], v[196:199], v[24:27]
	v_mfma_f32_16x16x32_bf16 v[20:23], v[172:175], v[196:199], v[20:23]
	v_mfma_f32_16x16x32_bf16 v[8:11], v[164:167], v[210:213], v[8:11]
	v_mfma_f32_16x16x32_bf16 v[4:7], v[172:175], v[210:213], v[4:7]
	v_mfma_f32_16x16x32_bf16 v[56:59], v[168:171], v[184:187], v[56:59]
	v_mfma_f32_16x16x32_bf16 v[52:55], v[176:179], v[184:187], v[52:55]
	v_mfma_f32_16x16x32_bf16 v[40:43], v[168:171], v[192:195], v[40:43]
	v_mfma_f32_16x16x32_bf16 v[36:39], v[176:179], v[192:195], v[36:39]
	v_mfma_f32_16x16x32_bf16 v[24:27], v[168:171], v[200:203], v[24:27]
	v_mfma_f32_16x16x32_bf16 v[20:23], v[176:179], v[200:203], v[20:23]
	v_mfma_f32_16x16x32_bf16 v[8:11], v[168:171], v[214:217], v[8:11]
	v_mfma_f32_16x16x32_bf16 v[4:7], v[176:179], v[214:217], v[4:7]
	s_barrier
	s_setprio 0
	s_add_u32 s76, vcc_lo, 0x80000
	s_addc_u32 s77, vcc_hi, 0
	s_mov_b32 m0, s62
	s_nop 0
	global_load_lds_dwordx4 v136, s[76:77]
	s_mov_b32 m0, s63
	s_nop 0
	global_load_lds_dwordx4 v134, s[76:77]
	ds_read_b128 v[148:151], v248
	ds_read_b128 v[152:155], v248 offset:1024
	ds_read_b128 v[156:159], v248 offset:2048
	ds_read_b128 v[160:163], v248 offset:3072
	ds_read_b128 v[164:167], v249
	ds_read_b128 v[168:171], v249 offset:1024
	ds_read_b128 v[172:175], v249 offset:2048
	ds_read_b128 v[176:179], v249 offset:3072
	ds_read_b128 v[180:183], v146 offset:32768
	ds_read_b128 v[184:187], v146 offset:33792
	ds_read_b128 v[188:191], v146 offset:34816
	ds_read_b128 v[192:195], v146 offset:35840
	ds_read_b128 v[196:199], v146 offset:36864
	ds_read_b128 v[200:203], v146 offset:37888
	ds_read_b128 v[210:213], v146 offset:38912
	ds_read_b128 v[214:217], v146 offset:39936
	s_waitcnt vmcnt(8)
	s_waitcnt lgkmcnt(0)
	s_setprio 1
	s_barrier
	v_mfma_f32_16x16x32_bf16 v[128:131], v[148:151], v[180:183], v[128:131]
	v_mfma_f32_16x16x32_bf16 v[124:127], v[156:159], v[180:183], v[124:127]
	v_mfma_f32_16x16x32_bf16 v[112:115], v[148:151], v[188:191], v[112:115]
	v_mfma_f32_16x16x32_bf16 v[108:111], v[156:159], v[188:191], v[108:111]
	v_mfma_f32_16x16x32_bf16 v[96:99], v[148:151], v[196:199], v[96:99]
	v_mfma_f32_16x16x32_bf16 v[92:95], v[156:159], v[196:199], v[92:95]
	v_mfma_f32_16x16x32_bf16 v[80:83], v[148:151], v[210:213], v[80:83]
	v_mfma_f32_16x16x32_bf16 v[76:79], v[156:159], v[210:213], v[76:79]
	v_mfma_f32_16x16x32_bf16 v[128:131], v[152:155], v[184:187], v[128:131]
	v_mfma_f32_16x16x32_bf16 v[124:127], v[160:163], v[184:187], v[124:127]
	v_mfma_f32_16x16x32_bf16 v[112:115], v[152:155], v[192:195], v[112:115]
	v_mfma_f32_16x16x32_bf16 v[108:111], v[160:163], v[192:195], v[108:111]
	v_mfma_f32_16x16x32_bf16 v[96:99], v[152:155], v[200:203], v[96:99]
	v_mfma_f32_16x16x32_bf16 v[92:95], v[160:163], v[200:203], v[92:95]
	v_mfma_f32_16x16x32_bf16 v[80:83], v[152:155], v[214:217], v[80:83]
	v_mfma_f32_16x16x32_bf16 v[76:79], v[160:163], v[214:217], v[76:79]
	v_mfma_f32_16x16x32_bf16 v[120:123], v[164:167], v[180:183], v[120:123]
	v_mfma_f32_16x16x32_bf16 v[116:119], v[172:175], v[180:183], v[116:119]
	v_mfma_f32_16x16x32_bf16 v[104:107], v[164:167], v[188:191], v[104:107]
	v_mfma_f32_16x16x32_bf16 v[100:103], v[172:175], v[188:191], v[100:103]
	v_mfma_f32_16x16x32_bf16 v[88:91], v[164:167], v[196:199], v[88:91]
	v_mfma_f32_16x16x32_bf16 v[84:87], v[172:175], v[196:199], v[84:87]
	v_mfma_f32_16x16x32_bf16 v[72:75], v[164:167], v[210:213], v[72:75]
	v_mfma_f32_16x16x32_bf16 v[68:71], v[172:175], v[210:213], v[68:71]
	v_mfma_f32_16x16x32_bf16 v[120:123], v[168:171], v[184:187], v[120:123]
	v_mfma_f32_16x16x32_bf16 v[116:119], v[176:179], v[184:187], v[116:119]
	v_mfma_f32_16x16x32_bf16 v[104:107], v[168:171], v[192:195], v[104:107]
	v_mfma_f32_16x16x32_bf16 v[100:103], v[176:179], v[192:195], v[100:103]
	v_mfma_f32_16x16x32_bf16 v[88:91], v[168:171], v[200:203], v[88:91]
	v_mfma_f32_16x16x32_bf16 v[84:87], v[176:179], v[200:203], v[84:87]
	v_mfma_f32_16x16x32_bf16 v[72:75], v[168:171], v[214:217], v[72:75]
	v_mfma_f32_16x16x32_bf16 v[68:71], v[176:179], v[214:217], v[68:71]
	s_barrier
	s_setprio 0
	s_add_i32 s57, s97, s35
	s_mov_b32 m0, s57
	s_nop 0
	s_add_u32 s98, s90, 0x80
	s_addc_u32 s99, s91, 0
	s_nop 0
	global_load_lds_dwordx4 v2, s[98:99]
	s_add_i32 m0, s57, 0x2000
	s_add_u32 s76, s90, 0x80080
	s_addc_u32 s77, s91, 0
	s_add_i32 s57, s48, s35
	global_load_lds_dwordx4 v132, s[98:99]
	s_mov_b32 m0, s57
	s_nop 0
	global_load_lds_dwordx4 v2, s[76:77]
	s_add_i32 m0, s57, 0x2000
	s_nop 0
	global_load_lds_dwordx4 v132, s[76:77]
	s_mov_b32 m0, s64
	s_nop 0
	s_add_u32 s98, vcc_lo, 0x80
	s_addc_u32 s99, vcc_hi, 0
	s_nop 0
	global_load_lds_dwordx4 v136, s[98:99]
	s_mov_b32 m0, s58
	s_nop 0
	global_load_lds_dwordx4 v134, s[98:99]
	ds_read_b128 v[180:183], v146 offset:49152
	ds_read_b128 v[184:187], v146 offset:50176
	ds_read_b128 v[188:191], v146 offset:51200
	ds_read_b128 v[192:195], v146 offset:52224
	ds_read_b128 v[196:199], v146 offset:53248
	ds_read_b128 v[200:203], v146 offset:54272
	ds_read_b128 v[210:213], v146 offset:55296
	ds_read_b128 v[214:217], v146 offset:56320
	s_waitcnt vmcnt(8)
	s_waitcnt lgkmcnt(0)
	s_setprio 1
	s_barrier
	v_mfma_f32_16x16x32_bf16 v[64:67], v[148:151], v[180:183], v[64:67]
	v_mfma_f32_16x16x32_bf16 v[60:63], v[156:159], v[180:183], v[60:63]
	v_mfma_f32_16x16x32_bf16 v[48:51], v[148:151], v[188:191], v[48:51]
	v_mfma_f32_16x16x32_bf16 v[44:47], v[156:159], v[188:191], v[44:47]
	v_mfma_f32_16x16x32_bf16 v[32:35], v[148:151], v[196:199], v[32:35]
	v_mfma_f32_16x16x32_bf16 v[28:31], v[156:159], v[196:199], v[28:31]
	v_mfma_f32_16x16x32_bf16 v[16:19], v[148:151], v[210:213], v[16:19]
	v_mfma_f32_16x16x32_bf16 v[12:15], v[156:159], v[210:213], v[12:15]
	v_mfma_f32_16x16x32_bf16 v[64:67], v[152:155], v[184:187], v[64:67]
	v_mfma_f32_16x16x32_bf16 v[60:63], v[160:163], v[184:187], v[60:63]
	v_mfma_f32_16x16x32_bf16 v[48:51], v[152:155], v[192:195], v[48:51]
	v_mfma_f32_16x16x32_bf16 v[44:47], v[160:163], v[192:195], v[44:47]
	v_mfma_f32_16x16x32_bf16 v[32:35], v[152:155], v[200:203], v[32:35]
	v_mfma_f32_16x16x32_bf16 v[28:31], v[160:163], v[200:203], v[28:31]
	v_mfma_f32_16x16x32_bf16 v[16:19], v[152:155], v[214:217], v[16:19]
	v_mfma_f32_16x16x32_bf16 v[12:15], v[160:163], v[214:217], v[12:15]
	v_mfma_f32_16x16x32_bf16 v[56:59], v[164:167], v[180:183], v[56:59]
	v_mfma_f32_16x16x32_bf16 v[52:55], v[172:175], v[180:183], v[52:55]
	v_mfma_f32_16x16x32_bf16 v[40:43], v[164:167], v[188:191], v[40:43]
	v_mfma_f32_16x16x32_bf16 v[36:39], v[172:175], v[188:191], v[36:39]
	v_mfma_f32_16x16x32_bf16 v[24:27], v[164:167], v[196:199], v[24:27]
	v_mfma_f32_16x16x32_bf16 v[20:23], v[172:175], v[196:199], v[20:23]
	v_mfma_f32_16x16x32_bf16 v[8:11], v[164:167], v[210:213], v[8:11]
	v_mfma_f32_16x16x32_bf16 v[4:7], v[172:175], v[210:213], v[4:7]
	v_mfma_f32_16x16x32_bf16 v[56:59], v[168:171], v[184:187], v[56:59]
	v_mfma_f32_16x16x32_bf16 v[52:55], v[176:179], v[184:187], v[52:55]
	v_mfma_f32_16x16x32_bf16 v[40:43], v[168:171], v[192:195], v[40:43]
	v_mfma_f32_16x16x32_bf16 v[36:39], v[176:179], v[192:195], v[36:39]
	v_mfma_f32_16x16x32_bf16 v[24:27], v[168:171], v[200:203], v[24:27]
	v_mfma_f32_16x16x32_bf16 v[20:23], v[176:179], v[200:203], v[20:23]
	v_mfma_f32_16x16x32_bf16 v[8:11], v[168:171], v[214:217], v[8:11]
	v_mfma_f32_16x16x32_bf16 v[4:7], v[176:179], v[214:217], v[4:7]
	s_barrier
	s_setprio 0
	s_add_i32 s56, s56, 2
	s_add_u32 s88, s88, 0x100
	s_addc_u32 s89, s89, 0
	s_add_u32 s54, s54, 0x100
	s_addc_u32 s55, s55, 0
	s_cmp_gt_u32 s56, 29
	s_cbranch_scc0 .LBB0_694
	s_and_b64 vcc, exec, s[68:69]
	s_cbranch_vccz .LBB0_697
	s_barrier
	s_setprio 2

.LBB0_700:
	s_setprio 0
	s_waitcnt vmcnt(0)
	s_barrier

.LBB0_763:
	s_add_i32 s56, s55, 2
	s_add_u32 s57, s84, 0xffe00080
	s_addc_u32 s62, s85, -1
	s_add_i32 m0, s16, 0xc000
	s_add_i32 s63, s16, 0xe000
	global_load_lds_dwordx4 v138, s[84:85]
	s_mov_b32 m0, s63
	s_cmp_eq_u32 s23, s55
	global_load_lds_dwordx4 v140, s[84:85]
	s_cselect_b32 s89, s73, s62
	s_cselect_b32 s88, s72, s57
	s_cselect_b32 s87, s75, s35
	s_cselect_b32 s86, s74, s29
	ds_read_b128 v[146:149], v246
	ds_read_b128 v[150:153], v246 offset:1024
	ds_read_b128 v[154:157], v246 offset:2048
	ds_read_b128 v[158:161], v246 offset:3072
	ds_read_b128 v[162:165], v247
	ds_read_b128 v[166:169], v247 offset:1024
	ds_read_b128 v[170:173], v247 offset:2048
	ds_read_b128 v[174:177], v247 offset:3072
	ds_read_b128 v[178:181], v144
	ds_read_b128 v[182:185], v144 offset:1024
	ds_read_b128 v[186:189], v144 offset:2048
	ds_read_b128 v[190:193], v144 offset:3072
	ds_read_b128 v[194:197], v144 offset:4096
	ds_read_b128 v[198:201], v144 offset:5120
	ds_read_b128 v[202:205], v144 offset:6144
	ds_read_b128 v[210:213], v144 offset:7168
	s_waitcnt vmcnt(8)
	s_waitcnt lgkmcnt(0)
	s_setprio 1
	s_barrier
	v_mfma_f32_16x16x32_bf16 v[128:131], v[146:149], v[178:181], v[128:131]
	v_mfma_f32_16x16x32_bf16 v[124:127], v[154:157], v[178:181], v[124:127]
	v_mfma_f32_16x16x32_bf16 v[120:123], v[146:149], v[186:189], v[120:123]
	v_mfma_f32_16x16x32_bf16 v[116:119], v[154:157], v[186:189], v[116:119]
	v_mfma_f32_16x16x32_bf16 v[104:107], v[146:149], v[194:197], v[104:107]
	v_mfma_f32_16x16x32_bf16 v[100:103], v[154:157], v[194:197], v[100:103]
	v_mfma_f32_16x16x32_bf16 v[88:91], v[146:149], v[202:205], v[88:91]
	v_mfma_f32_16x16x32_bf16 v[84:87], v[154:157], v[202:205], v[84:87]
	v_mfma_f32_16x16x32_bf16 v[128:131], v[150:153], v[182:185], v[128:131]
	v_mfma_f32_16x16x32_bf16 v[124:127], v[158:161], v[182:185], v[124:127]
	v_mfma_f32_16x16x32_bf16 v[120:123], v[150:153], v[190:193], v[120:123]
	v_mfma_f32_16x16x32_bf16 v[116:119], v[158:161], v[190:193], v[116:119]
	v_mfma_f32_16x16x32_bf16 v[104:107], v[150:153], v[198:201], v[104:107]
	v_mfma_f32_16x16x32_bf16 v[100:103], v[158:161], v[198:201], v[100:103]
	v_mfma_f32_16x16x32_bf16 v[88:91], v[150:153], v[210:213], v[88:91]
	v_mfma_f32_16x16x32_bf16 v[84:87], v[158:161], v[210:213], v[84:87]
	v_mfma_f32_16x16x32_bf16 v[112:115], v[162:165], v[178:181], v[112:115]
	v_mfma_f32_16x16x32_bf16 v[108:111], v[170:173], v[178:181], v[108:111]
	v_mfma_f32_16x16x32_bf16 v[96:99], v[162:165], v[186:189], v[96:99]
	v_mfma_f32_16x16x32_bf16 v[92:95], v[170:173], v[186:189], v[92:95]
	v_mfma_f32_16x16x32_bf16 v[80:83], v[162:165], v[194:197], v[80:83]
	v_mfma_f32_16x16x32_bf16 v[76:79], v[170:173], v[194:197], v[76:79]
	v_mfma_f32_16x16x32_bf16 v[72:75], v[162:165], v[202:205], v[72:75]
	v_mfma_f32_16x16x32_bf16 v[68:71], v[170:173], v[202:205], v[68:71]
	v_mfma_f32_16x16x32_bf16 v[112:115], v[166:169], v[182:185], v[112:115]
	v_mfma_f32_16x16x32_bf16 v[108:111], v[174:177], v[182:185], v[108:111]
	v_mfma_f32_16x16x32_bf16 v[96:99], v[166:169], v[190:193], v[96:99]
	v_mfma_f32_16x16x32_bf16 v[92:95], v[174:177], v[190:193], v[92:95]
	v_mfma_f32_16x16x32_bf16 v[80:83], v[166:169], v[198:201], v[80:83]
	v_mfma_f32_16x16x32_bf16 v[76:79], v[174:177], v[198:201], v[76:79]
	v_mfma_f32_16x16x32_bf16 v[72:75], v[166:169], v[210:213], v[72:75]
	v_mfma_f32_16x16x32_bf16 v[68:71], v[174:177], v[210:213], v[68:71]
	s_barrier
	s_setprio 0
	s_add_i32 s55, s33, s13
	s_mov_b32 m0, s55
	s_nop 0
	global_load_lds_dwordx4 v2, s[86:87]
	s_add_i32 m0, s55, 0x2000
	s_add_u32 s62, s86, 0x200000
	s_addc_u32 s63, s87, 0
	s_add_i32 s55, s96, s13
	global_load_lds_dwordx4 v136, s[86:87]
	s_mov_b32 m0, s55
	s_nop 0
	global_load_lds_dwordx4 v2, s[62:63]
	s_add_i32 m0, s55, 0x2000
	s_nop 0
	global_load_lds_dwordx4 v136, s[62:63]
	s_mov_b32 m0, s16
	s_nop 0
	global_load_lds_dwordx4 v132, s[88:89]
	s_mov_b32 m0, s17
	s_nop 0
	global_load_lds_dwordx4 v134, s[88:89]
	ds_read_b128 v[178:181], v144 offset:16384
	ds_read_b128 v[182:185], v144 offset:17408
	ds_read_b128 v[186:189], v144 offset:18432
	ds_read_b128 v[190:193], v144 offset:19456
	ds_read_b128 v[194:197], v144 offset:20480
	ds_read_b128 v[198:201], v144 offset:21504
	ds_read_b128 v[202:205], v144 offset:22528
	ds_read_b128 v[210:213], v144 offset:23552
	s_waitcnt vmcnt(8)
	s_waitcnt lgkmcnt(0)
	s_setprio 1
	s_barrier
	v_mfma_f32_16x16x32_bf16 v[64:67], v[146:149], v[178:181], v[64:67]
	v_mfma_f32_16x16x32_bf16 v[60:63], v[154:157], v[178:181], v[60:63]
	v_mfma_f32_16x16x32_bf16 v[56:59], v[146:149], v[186:189], v[56:59]
	v_mfma_f32_16x16x32_bf16 v[52:55], v[154:157], v[186:189], v[52:55]
	v_mfma_f32_16x16x32_bf16 v[40:43], v[146:149], v[194:197], v[40:43]
	v_mfma_f32_16x16x32_bf16 v[36:39], v[154:157], v[194:197], v[36:39]
	v_mfma_f32_16x16x32_bf16 v[24:27], v[146:149], v[202:205], v[24:27]
	v_mfma_f32_16x16x32_bf16 v[20:23], v[154:157], v[202:205], v[20:23]
	v_mfma_f32_16x16x32_bf16 v[64:67], v[150:153], v[182:185], v[64:67]
	v_mfma_f32_16x16x32_bf16 v[60:63], v[158:161], v[182:185], v[60:63]
	v_mfma_f32_16x16x32_bf16 v[56:59], v[150:153], v[190:193], v[56:59]
	v_mfma_f32_16x16x32_bf16 v[52:55], v[158:161], v[190:193], v[52:55]
	v_mfma_f32_16x16x32_bf16 v[40:43], v[150:153], v[198:201], v[40:43]
	v_mfma_f32_16x16x32_bf16 v[36:39], v[158:161], v[198:201], v[36:39]
	v_mfma_f32_16x16x32_bf16 v[24:27], v[150:153], v[210:213], v[24:27]
	v_mfma_f32_16x16x32_bf16 v[20:23], v[158:161], v[210:213], v[20:23]
	v_mfma_f32_16x16x32_bf16 v[48:51], v[162:165], v[178:181], v[48:51]
	v_mfma_f32_16x16x32_bf16 v[44:47], v[170:173], v[178:181], v[44:47]
	v_mfma_f32_16x16x32_bf16 v[32:35], v[162:165], v[186:189], v[32:35]
	v_mfma_f32_16x16x32_bf16 v[28:31], v[170:173], v[186:189], v[28:31]
	v_mfma_f32_16x16x32_bf16 v[16:19], v[162:165], v[194:197], v[16:19]
	v_mfma_f32_16x16x32_bf16 v[12:15], v[170:173], v[194:197], v[12:15]
	v_mfma_f32_16x16x32_bf16 v[8:11], v[162:165], v[202:205], v[8:11]
	v_mfma_f32_16x16x32_bf16 v[4:7], v[170:173], v[202:205], v[4:7]
	v_mfma_f32_16x16x32_bf16 v[48:51], v[166:169], v[182:185], v[48:51]
	v_mfma_f32_16x16x32_bf16 v[44:47], v[174:177], v[182:185], v[44:47]
	v_mfma_f32_16x16x32_bf16 v[32:35], v[166:169], v[190:193], v[32:35]
	v_mfma_f32_16x16x32_bf16 v[28:31], v[174:177], v[190:193], v[28:31]
	v_mfma_f32_16x16x32_bf16 v[16:19], v[166:169], v[198:201], v[16:19]
	v_mfma_f32_16x16x32_bf16 v[12:15], v[174:177], v[198:201], v[12:15]
	v_mfma_f32_16x16x32_bf16 v[8:11], v[166:169], v[210:213], v[8:11]
	v_mfma_f32_16x16x32_bf16 v[4:7], v[174:177], v[210:213], v[4:7]
	s_barrier
	s_setprio 0
	s_add_u32 s62, s88, 0x200000
	s_addc_u32 s63, s89, 0
	s_mov_b32 m0, s58
	s_nop 0
	global_load_lds_dwordx4 v132, s[62:63]
	s_mov_b32 m0, s59
	s_nop 0
	global_load_lds_dwordx4 v134, s[62:63]
	ds_read_b128 v[146:149], v248
	ds_read_b128 v[150:153], v248 offset:1024
	ds_read_b128 v[154:157], v248 offset:2048
	ds_read_b128 v[158:161], v248 offset:3072
	ds_read_b128 v[162:165], v249
	ds_read_b128 v[166:169], v249 offset:1024
	ds_read_b128 v[170:173], v249 offset:2048
	ds_read_b128 v[174:177], v249 offset:3072
	ds_read_b128 v[178:181], v144 offset:32768
	ds_read_b128 v[182:185], v144 offset:33792
	ds_read_b128 v[186:189], v144 offset:34816
	ds_read_b128 v[190:193], v144 offset:35840
	ds_read_b128 v[194:197], v144 offset:36864
	ds_read_b128 v[198:201], v144 offset:37888
	ds_read_b128 v[202:205], v144 offset:38912
	ds_read_b128 v[210:213], v144 offset:39936
	s_waitcnt vmcnt(8)
	s_waitcnt lgkmcnt(0)
	s_setprio 1
	s_barrier
	v_mfma_f32_16x16x32_bf16 v[128:131], v[146:149], v[178:181], v[128:131]
	v_mfma_f32_16x16x32_bf16 v[124:127], v[154:157], v[178:181], v[124:127]
	v_mfma_f32_16x16x32_bf16 v[120:123], v[146:149], v[186:189], v[120:123]
	v_mfma_f32_16x16x32_bf16 v[116:119], v[154:157], v[186:189], v[116:119]
	v_mfma_f32_16x16x32_bf16 v[104:107], v[146:149], v[194:197], v[104:107]
	v_mfma_f32_16x16x32_bf16 v[100:103], v[154:157], v[194:197], v[100:103]
	v_mfma_f32_16x16x32_bf16 v[88:91], v[146:149], v[202:205], v[88:91]
	v_mfma_f32_16x16x32_bf16 v[84:87], v[154:157], v[202:205], v[84:87]
	v_mfma_f32_16x16x32_bf16 v[128:131], v[150:153], v[182:185], v[128:131]
	v_mfma_f32_16x16x32_bf16 v[124:127], v[158:161], v[182:185], v[124:127]
	v_mfma_f32_16x16x32_bf16 v[120:123], v[150:153], v[190:193], v[120:123]
	v_mfma_f32_16x16x32_bf16 v[116:119], v[158:161], v[190:193], v[116:119]
	v_mfma_f32_16x16x32_bf16 v[104:107], v[150:153], v[198:201], v[104:107]
	v_mfma_f32_16x16x32_bf16 v[100:103], v[158:161], v[198:201], v[100:103]
	v_mfma_f32_16x16x32_bf16 v[88:91], v[150:153], v[210:213], v[88:91]
	v_mfma_f32_16x16x32_bf16 v[84:87], v[158:161], v[210:213], v[84:87]
	v_mfma_f32_16x16x32_bf16 v[112:115], v[162:165], v[178:181], v[112:115]
	v_mfma_f32_16x16x32_bf16 v[108:111], v[170:173], v[178:181], v[108:111]
	v_mfma_f32_16x16x32_bf16 v[96:99], v[162:165], v[186:189], v[96:99]
	v_mfma_f32_16x16x32_bf16 v[92:95], v[170:173], v[186:189], v[92:95]
	v_mfma_f32_16x16x32_bf16 v[80:83], v[162:165], v[194:197], v[80:83]
	v_mfma_f32_16x16x32_bf16 v[76:79], v[170:173], v[194:197], v[76:79]
	v_mfma_f32_16x16x32_bf16 v[72:75], v[162:165], v[202:205], v[72:75]
	v_mfma_f32_16x16x32_bf16 v[68:71], v[170:173], v[202:205], v[68:71]
	v_mfma_f32_16x16x32_bf16 v[112:115], v[166:169], v[182:185], v[112:115]
	v_mfma_f32_16x16x32_bf16 v[108:111], v[174:177], v[182:185], v[108:111]
	v_mfma_f32_16x16x32_bf16 v[96:99], v[166:169], v[190:193], v[96:99]
	v_mfma_f32_16x16x32_bf16 v[92:95], v[174:177], v[190:193], v[92:95]
	v_mfma_f32_16x16x32_bf16 v[80:83], v[166:169], v[198:201], v[80:83]
	v_mfma_f32_16x16x32_bf16 v[76:79], v[174:177], v[198:201], v[76:79]
	v_mfma_f32_16x16x32_bf16 v[72:75], v[166:169], v[210:213], v[72:75]
	v_mfma_f32_16x16x32_bf16 v[68:71], v[174:177], v[210:213], v[68:71]
	s_barrier
	s_setprio 0
	s_add_i32 s55, s97, s13
	s_mov_b32 m0, s55
	s_nop 0
	s_add_u32 s98, s86, 0x80
	s_addc_u32 s99, s87, 0
	s_nop 0
	global_load_lds_dwordx4 v2, s[98:99]
	s_add_i32 m0, s55, 0x2000
	s_add_u32 s62, s86, 0x200080
	s_addc_u32 s63, s87, 0
	s_add_i32 s55, s48, s13
	global_load_lds_dwordx4 v136, s[98:99]
	s_mov_b32 m0, s55
	s_nop 0
	global_load_lds_dwordx4 v2, s[62:63]
	s_add_i32 m0, s55, 0x2000
	s_nop 0
	global_load_lds_dwordx4 v136, s[62:63]
	s_mov_b32 m0, s60
	s_nop 0
	s_add_u32 s98, s88, 0x80
	s_addc_u32 s99, s89, 0
	s_nop 0
	global_load_lds_dwordx4 v132, s[98:99]
	s_mov_b32 m0, s61
	s_nop 0
	global_load_lds_dwordx4 v134, s[98:99]
	ds_read_b128 v[178:181], v144 offset:49152
	ds_read_b128 v[182:185], v144 offset:50176
	ds_read_b128 v[186:189], v144 offset:51200
	ds_read_b128 v[190:193], v144 offset:52224
	ds_read_b128 v[194:197], v144 offset:53248
	ds_read_b128 v[198:201], v144 offset:54272
	ds_read_b128 v[202:205], v144 offset:55296
	ds_read_b128 v[210:213], v144 offset:56320
	s_waitcnt vmcnt(8)
	s_waitcnt lgkmcnt(0)
	s_setprio 1
	s_barrier
	v_mfma_f32_16x16x32_bf16 v[64:67], v[146:149], v[178:181], v[64:67]
	v_mfma_f32_16x16x32_bf16 v[60:63], v[154:157], v[178:181], v[60:63]
	v_mfma_f32_16x16x32_bf16 v[56:59], v[146:149], v[186:189], v[56:59]
	v_mfma_f32_16x16x32_bf16 v[52:55], v[154:157], v[186:189], v[52:55]
	v_mfma_f32_16x16x32_bf16 v[40:43], v[146:149], v[194:197], v[40:43]
	v_mfma_f32_16x16x32_bf16 v[36:39], v[154:157], v[194:197], v[36:39]
	v_mfma_f32_16x16x32_bf16 v[24:27], v[146:149], v[202:205], v[24:27]
	v_mfma_f32_16x16x32_bf16 v[20:23], v[154:157], v[202:205], v[20:23]
	v_mfma_f32_16x16x32_bf16 v[64:67], v[150:153], v[182:185], v[64:67]
	v_mfma_f32_16x16x32_bf16 v[60:63], v[158:161], v[182:185], v[60:63]
	v_mfma_f32_16x16x32_bf16 v[56:59], v[150:153], v[190:193], v[56:59]
	v_mfma_f32_16x16x32_bf16 v[52:55], v[158:161], v[190:193], v[52:55]
	v_mfma_f32_16x16x32_bf16 v[40:43], v[150:153], v[198:201], v[40:43]
	v_mfma_f32_16x16x32_bf16 v[36:39], v[158:161], v[198:201], v[36:39]
	v_mfma_f32_16x16x32_bf16 v[24:27], v[150:153], v[210:213], v[24:27]
	v_mfma_f32_16x16x32_bf16 v[20:23], v[158:161], v[210:213], v[20:23]
	v_mfma_f32_16x16x32_bf16 v[48:51], v[162:165], v[178:181], v[48:51]
	v_mfma_f32_16x16x32_bf16 v[44:47], v[170:173], v[178:181], v[44:47]
	v_mfma_f32_16x16x32_bf16 v[32:35], v[162:165], v[186:189], v[32:35]
	v_mfma_f32_16x16x32_bf16 v[28:31], v[170:173], v[186:189], v[28:31]
	v_mfma_f32_16x16x32_bf16 v[16:19], v[162:165], v[194:197], v[16:19]
	v_mfma_f32_16x16x32_bf16 v[12:15], v[170:173], v[194:197], v[12:15]
	v_mfma_f32_16x16x32_bf16 v[8:11], v[162:165], v[202:205], v[8:11]
	v_mfma_f32_16x16x32_bf16 v[4:7], v[170:173], v[202:205], v[4:7]
	v_mfma_f32_16x16x32_bf16 v[48:51], v[166:169], v[182:185], v[48:51]
	v_mfma_f32_16x16x32_bf16 v[44:47], v[174:177], v[182:185], v[44:47]
	v_mfma_f32_16x16x32_bf16 v[32:35], v[166:169], v[190:193], v[32:35]
	v_mfma_f32_16x16x32_bf16 v[28:31], v[174:177], v[190:193], v[28:31]
	v_mfma_f32_16x16x32_bf16 v[16:19], v[166:169], v[198:201], v[16:19]
	v_mfma_f32_16x16x32_bf16 v[12:15], v[174:177], v[198:201], v[12:15]
	v_mfma_f32_16x16x32_bf16 v[8:11], v[166:169], v[210:213], v[8:11]
	v_mfma_f32_16x16x32_bf16 v[4:7], v[174:177], v[210:213], v[4:7]
	s_barrier
	s_setprio 0
	s_add_u32 s84, s84, 0x100
	s_addc_u32 s85, s85, 0
	s_add_u32 s29, s29, 0x100
	s_addc_u32 s35, s35, 0
	s_cmp_ge_u32 s56, s51
	s_mov_b32 s55, s56
	s_cbranch_scc0 .LBB0_763
	s_and_b64 vcc, exec, s[68:69]
	s_cbranch_vccz .LBB0_766
	s_barrier
	s_setprio 2

.LBB0_769:
	s_setprio 0
	s_lshl_b64 s[0:1], s[78:79], 2
	v_readlane_b32 s72, v253, 7
	s_add_i32 s9, s49, 1
	v_readlane_b32 s78, v253, 13
	s_waitcnt vmcnt(0)
	v_readlane_b32 s79, v253, 14
	v_readlane_b32 s80, v253, 15
	v_readlane_b32 s81, v253, 16
	s_add_u32 s0, s78, s0
	v_readlane_b32 s82, v253, 17
	v_readlane_b32 s83, v253, 18
	s_addc_u32 s1, s79, s1
	v_readlane_b32 s50, v252, 52
	v_readlane_b32 s80, v252, 48
	v_readlane_b32 s56, v252, 55
	s_cmp_eq_u32 s49, 3
	s_mov_b64 s[36:37], -1
	v_readlane_b32 s51, v252, 53
	v_readlane_b32 s81, v252, 49
	v_readlane_b32 s82, v252, 50
	v_readlane_b32 s83, v252, 51
	v_readlane_b32 s57, v252, 56
	s_barrier
	v_readlane_b32 s73, v253, 8
	v_readlane_b32 s74, v253, 9
	v_readlane_b32 s75, v253, 10
	v_readlane_b32 s76, v253, 11
	v_readlane_b32 s77, v253, 12
	v_readlane_b32 s84, v253, 19
	v_readlane_b32 s85, v253, 20
	v_readlane_b32 s86, v253, 21
	v_readlane_b32 s87, v253, 22
	s_cbranch_scc1 .LBB0_812
	v_mov_b32_e32 v1, v0
	s_waitcnt vmcnt(0)
	s_waitcnt vmcnt(0)
	v_readfirstlane_b32 s23, v1
	s_cmp_lt_u32 s23, 64
	s_barrier
	s_cbranch_scc1 .LBB0_800
	s_lshl_b32 s64, s9, 11
	s_lshl_b64 s[12:13], s[64:65], 2
	v_readlane_b32 s72, v253, 7
	v_readlane_b32 s73, v253, 8
	s_add_u32 s36, s72, s12
	s_mul_i32 s64, s49, 3
	s_movk_i32 s12, 0x1840
	s_addc_u32 s37, s73, s13
	s_add_i32 s58, s64, 3
	s_mov_b32 s59, s65
	v_cmp_gt_i32_e32 vcc, s12, v1
	v_lshl_add_u32 v2, v1, 2, 0
	v_readlane_b32 s74, v253, 9
	v_readlane_b32 s75, v253, 10
	v_readlane_b32 s76, v253, 11
	v_readlane_b32 s77, v253, 12
	v_readlane_b32 s78, v253, 13
	v_readlane_b32 s79, v253, 14
	v_readlane_b32 s80, v253, 15
	v_readlane_b32 s81, v253, 16
	v_readlane_b32 s82, v253, 17
	v_readlane_b32 s83, v253, 18
	v_readlane_b32 s84, v253, 19
	v_readlane_b32 s85, v253, 20
	v_readlane_b32 s86, v253, 21
	v_readlane_b32 s87, v253, 22
	v_readlane_b32 s80, v252, 48
	v_readlane_b32 s81, v252, 49
	v_readlane_b32 s82, v252, 50
	v_readlane_b32 s83, v252, 51
	s_mul_i32 s12, s64, 0xc000
	s_add_u32 s12, s50, s12
	s_addc_u32 s13, s51, 0
	s_add_u32 s16, s12, 0xa000
	s_addc_u32 s17, s13, 0
	s_add_u32 s12, s12, 0x24000
	s_addc_u32 s13, s13, 0
	s_add_u32 s72, s12, 0x2000
	s_addc_u32 s73, s13, 0
	s_mov_b64 s[68:69], exec
	v_subrev_u32_e32 v4, 64, v1
	v_add_u32_e32 v5, 0xffffff00, v2
	v_add_u32_e32 v6, 0xc000, v5
	s_mov_b32 s58, 0xc000
	v_mov_b32_e32 v8, v4
	v_lshrrev_b32_e32 v9, 11, v8
	v_and_b32_e32 v8, 0x7ff, v8
	v_lshlrev_b32_e32 v8, 2, v8
	v_mad_u32_u24 v9, v9, s58, v8
	global_load_dword v10, v9, s[16:17]
	global_load_dword v11, v8, s[0:1]
	global_load_dword v12, v8, s[36:37]
	global_load_dword v13, v9, s[72:73]
	global_load_dword v14, v9, s[12:13]
	v_add_u32_e32 v16, 448, v4
	v_lshrrev_b32_e32 v17, 11, v16
	v_and_b32_e32 v16, 0x7ff, v16
	v_lshlrev_b32_e32 v16, 2, v16
	v_mad_u32_u24 v17, v17, s58, v16
	global_load_dword v18, v17, s[16:17]
	global_load_dword v19, v16, s[0:1]
	global_load_dword v20, v16, s[36:37]
	global_load_dword v21, v17, s[72:73]
	global_load_dword v22, v17, s[12:13]
	v_add_u32_e32 v24, 896, v4
	v_lshrrev_b32_e32 v25, 11, v24
	v_and_b32_e32 v24, 0x7ff, v24
	v_lshlrev_b32_e32 v24, 2, v24
	v_mad_u32_u24 v25, v25, s58, v24
	global_load_dword v26, v25, s[16:17]
	global_load_dword v27, v24, s[0:1]
	global_load_dword v28, v24, s[36:37]
	global_load_dword v29, v25, s[72:73]
	global_load_dword v30, v25, s[12:13]
	v_add_u32_e32 v32, 1344, v4
	v_lshrrev_b32_e32 v33, 11, v32
	v_and_b32_e32 v32, 0x7ff, v32
	v_lshlrev_b32_e32 v32, 2, v32
	v_mad_u32_u24 v33, v33, s58, v32
	global_load_dword v34, v33, s[16:17]
	global_load_dword v35, v32, s[0:1]
	global_load_dword v36, v32, s[36:37]
	global_load_dword v37, v33, s[72:73]
	global_load_dword v38, v33, s[12:13]
	v_add_u32_e32 v40, 1792, v4
	v_lshrrev_b32_e32 v41, 11, v40
	v_and_b32_e32 v40, 0x7ff, v40
	v_lshlrev_b32_e32 v40, 2, v40
	v_mad_u32_u24 v41, v41, s58, v40
	global_load_dword v42, v41, s[16:17]
	global_load_dword v43, v40, s[0:1]
	global_load_dword v44, v40, s[36:37]
	global_load_dword v45, v41, s[72:73]
	global_load_dword v46, v41, s[12:13]
	v_add_u32_e32 v48, 2240, v4
	v_lshrrev_b32_e32 v49, 11, v48
	v_and_b32_e32 v48, 0x7ff, v48
	v_lshlrev_b32_e32 v48, 2, v48
	v_mad_u32_u24 v49, v49, s58, v48
	global_load_dword v50, v49, s[16:17]
	global_load_dword v51, v48, s[0:1]
	global_load_dword v52, v48, s[36:37]
	global_load_dword v53, v49, s[72:73]
	global_load_dword v54, v49, s[12:13]
	v_add_u32_e32 v56, 2688, v4
	v_lshrrev_b32_e32 v57, 11, v56
	v_and_b32_e32 v56, 0x7ff, v56
	v_lshlrev_b32_e32 v56, 2, v56
	v_mad_u32_u24 v57, v57, s58, v56
	global_load_dword v58, v57, s[16:17]
	global_load_dword v59, v56, s[0:1]
	global_load_dword v60, v56, s[36:37]
	global_load_dword v61, v57, s[72:73]
	global_load_dword v62, v57, s[12:13]
	v_add_u32_e32 v64, 3136, v4
	v_lshrrev_b32_e32 v65, 11, v64
	v_and_b32_e32 v64, 0x7ff, v64
	v_lshlrev_b32_e32 v64, 2, v64
	v_mad_u32_u24 v65, v65, s58, v64
	global_load_dword v66, v65, s[16:17]
	global_load_dword v67, v64, s[0:1]
	global_load_dword v68, v64, s[36:37]
	global_load_dword v69, v65, s[72:73]
	global_load_dword v70, v65, s[12:13]
	v_add_u32_e32 v72, 3584, v4
	v_lshrrev_b32_e32 v73, 11, v72
	v_and_b32_e32 v72, 0x7ff, v72
	v_lshlrev_b32_e32 v72, 2, v72
	v_mad_u32_u24 v73, v73, s58, v72
	global_load_dword v74, v73, s[16:17]
	global_load_dword v75, v72, s[0:1]
	global_load_dword v76, v72, s[36:37]
	global_load_dword v77, v73, s[72:73]
	global_load_dword v78, v73, s[12:13]
	v_add_u32_e32 v80, 4032, v4
	v_lshrrev_b32_e32 v81, 11, v80
	v_and_b32_e32 v80, 0x7ff, v80
	v_lshlrev_b32_e32 v80, 2, v80
	v_mad_u32_u24 v81, v81, s58, v80
	global_load_dword v82, v81, s[16:17]
	global_load_dword v83, v80, s[0:1]
	global_load_dword v84, v80, s[36:37]
	global_load_dword v85, v81, s[72:73]
	global_load_dword v86, v81, s[12:13]
	v_add_u32_e32 v88, 4480, v4
	v_lshrrev_b32_e32 v89, 11, v88
	v_and_b32_e32 v88, 0x7ff, v88
	v_lshlrev_b32_e32 v88, 2, v88
	v_mad_u32_u24 v89, v89, s58, v88
	global_load_dword v90, v89, s[16:17]
	global_load_dword v91, v88, s[0:1]
	global_load_dword v92, v88, s[36:37]
	global_load_dword v93, v89, s[72:73]
	global_load_dword v94, v89, s[12:13]
	v_add_u32_e32 v96, 4928, v4
	v_lshrrev_b32_e32 v97, 11, v96
	v_and_b32_e32 v96, 0x7ff, v96
	v_lshlrev_b32_e32 v96, 2, v96
	v_mad_u32_u24 v97, v97, s58, v96
	global_load_dword v98, v97, s[16:17]
	global_load_dword v99, v96, s[0:1]
	global_load_dword v100, v96, s[36:37]
	global_load_dword v101, v97, s[72:73]
	global_load_dword v102, v97, s[12:13]
	s_waitcnt vmcnt(55)
	v_mul_f32_e32 v10, v10, v11
	v_add_f32_e32 v13, 1.0, v13
	v_mul_f32_e32 v13, v12, v13
	ds_write_b32 v5, v10 offset:0
	ds_write_b32 v5, v13 offset:24576
	ds_write_b32 v6, v14 offset:0
	v_add_u32_e32 v104, 5376, v4
	v_lshrrev_b32_e32 v105, 11, v104
	v_and_b32_e32 v104, 0x7ff, v104
	v_lshlrev_b32_e32 v104, 2, v104
	v_mad_u32_u24 v105, v105, s58, v104
	global_load_dword v106, v105, s[16:17]
	global_load_dword v107, v104, s[0:1]
	global_load_dword v108, v104, s[36:37]
	global_load_dword v109, v105, s[72:73]
	global_load_dword v110, v105, s[12:13]
	s_waitcnt vmcnt(55)
	v_mul_f32_e32 v18, v18, v19
	v_add_f32_e32 v21, 1.0, v21
	v_mul_f32_e32 v21, v20, v21
	ds_write_b32 v5, v18 offset:1792
	ds_write_b32 v5, v21 offset:26368
	ds_write_b32 v6, v22 offset:1792
	v_add_u32_e32 v112, 5824, v4
	v_lshrrev_b32_e32 v113, 11, v112
	v_and_b32_e32 v112, 0x7ff, v112
	v_lshlrev_b32_e32 v112, 2, v112
	v_mad_u32_u24 v113, v113, s58, v112
	global_load_dword v114, v113, s[16:17]
	global_load_dword v115, v112, s[0:1]
	global_load_dword v116, v112, s[36:37]
	global_load_dword v117, v113, s[72:73]
	global_load_dword v118, v113, s[12:13]
	s_waitcnt vmcnt(55)
	v_mul_f32_e32 v26, v26, v27
	v_add_f32_e32 v29, 1.0, v29
	v_mul_f32_e32 v29, v28, v29
	ds_write_b32 v5, v26 offset:3584
	ds_write_b32 v5, v29 offset:28160
	ds_write_b32 v6, v30 offset:3584
	s_waitcnt vmcnt(50)
	v_mul_f32_e32 v34, v34, v35
	v_add_f32_e32 v37, 1.0, v37
	v_mul_f32_e32 v37, v36, v37
	ds_write_b32 v5, v34 offset:5376
	ds_write_b32 v5, v37 offset:29952
	ds_write_b32 v6, v38 offset:5376
	s_waitcnt vmcnt(45)
	v_mul_f32_e32 v42, v42, v43
	v_add_f32_e32 v45, 1.0, v45
	v_mul_f32_e32 v45, v44, v45
	ds_write_b32 v5, v42 offset:7168
	ds_write_b32 v5, v45 offset:31744
	ds_write_b32 v6, v46 offset:7168
	s_waitcnt vmcnt(40)
	v_mul_f32_e32 v50, v50, v51
	v_add_f32_e32 v53, 1.0, v53
	v_mul_f32_e32 v53, v52, v53
	ds_write_b32 v5, v50 offset:8960
	ds_write_b32 v5, v53 offset:33536
	ds_write_b32 v6, v54 offset:8960
	s_waitcnt vmcnt(35)
	v_mul_f32_e32 v58, v58, v59
	v_add_f32_e32 v61, 1.0, v61
	v_mul_f32_e32 v61, v60, v61
	ds_write_b32 v5, v58 offset:10752
	ds_write_b32 v5, v61 offset:35328
	ds_write_b32 v6, v62 offset:10752
	s_waitcnt vmcnt(30)
	v_mul_f32_e32 v66, v66, v67
	v_add_f32_e32 v69, 1.0, v69
	v_mul_f32_e32 v69, v68, v69
	ds_write_b32 v5, v66 offset:12544
	ds_write_b32 v5, v69 offset:37120
	ds_write_b32 v6, v70 offset:12544
	s_waitcnt vmcnt(25)
	v_mul_f32_e32 v74, v74, v75
	v_add_f32_e32 v77, 1.0, v77
	v_mul_f32_e32 v77, v76, v77
	ds_write_b32 v5, v74 offset:14336
	ds_write_b32 v5, v77 offset:38912
	ds_write_b32 v6, v78 offset:14336
	s_waitcnt vmcnt(20)
	v_mul_f32_e32 v82, v82, v83
	v_add_f32_e32 v85, 1.0, v85
	v_mul_f32_e32 v85, v84, v85
	ds_write_b32 v5, v82 offset:16128
	ds_write_b32 v5, v85 offset:40704
	ds_write_b32 v6, v86 offset:16128
	s_waitcnt vmcnt(15)
	v_mul_f32_e32 v90, v90, v91
	v_add_f32_e32 v93, 1.0, v93
	v_mul_f32_e32 v93, v92, v93
	ds_write_b32 v5, v90 offset:17920
	ds_write_b32 v5, v93 offset:42496
	ds_write_b32 v6, v94 offset:17920
	s_waitcnt vmcnt(10)
	v_mul_f32_e32 v98, v98, v99
	v_add_f32_e32 v101, 1.0, v101
	v_mul_f32_e32 v101, v100, v101
	ds_write_b32 v5, v98 offset:19712
	ds_write_b32 v5, v101 offset:44288
	ds_write_b32 v6, v102 offset:19712
	s_waitcnt vmcnt(5)
	v_mul_f32_e32 v106, v106, v107
	v_add_f32_e32 v109, 1.0, v109
	v_mul_f32_e32 v109, v108, v109
	ds_write_b32 v5, v106 offset:21504
	ds_write_b32 v5, v109 offset:46080
	ds_write_b32 v6, v110 offset:21504
	s_waitcnt vmcnt(0)
	v_cmp_gt_u32_e32 vcc, 0x140, v4
	s_and_saveexec_b64 s[68:69], vcc
	s_cbranch_execz .Ltb_p7_p13
	v_mul_f32_e32 v114, v114, v115
	v_add_f32_e32 v117, 1.0, v117
	v_mul_f32_e32 v117, v116, v117
	ds_write_b32 v5, v114 offset:23296
	ds_write_b32 v5, v117 offset:47872
	ds_write_b32 v6, v118 offset:23296
